# GEMM K-loops: closing s_barrier of each MFMA burst moved ahead of the last MFMA (partner wave released one MFMA early)
# speedup vs baseline: 1.0085x; 1.0021x over previous
; #define PG8_STAGE(bufoff, gbase, voff) do { _Pragma("unroll") for (int _i = 0; _i < 2; ++_i) \
;         __builtin_amdgcn_global_load_lds((const unsigned*)((const char*)(gbase) + (voff)[_i]), (PG8_LAS unsigned*)(lds + (bufoff) + ldsw + _i * 8192), 16, 0, 0); } while (0)
; #define PG8_LDA(dst, b, h) do { _Pragma("unroll") for (int m = 0; m < 4; ++m) _Pragma("unroll") for (int k = 0; k < 2; ++k) dst[m][k] = *(const PG8_LAS bf16x8*)(lds + PG8_SA(b, h) + aoff + m * 2048 + k * 1024); } while (0)
; #define PG8_LDB(dst, b, h) do { _Pragma("unroll") for (int n = 0; n < 2; ++n) _Pragma("unroll") for (int k = 0; k < 2; ++k) dst[n][k] = *(const PG8_LAS bf16x8*)(lds + PG8_SB(b, h) + boff + n * 2048 + k * 1024); } while (0)
; #define PG8_WAIT_V(n) asm volatile("s_waitcnt vmcnt(" #n ")" ::: "memory")
; #define PG8_WAIT_L(n) asm volatile("s_waitcnt lgkmcnt(" #n ")" ::: "memory")
; #define PG8_BAR __builtin_amdgcn_s_barrier()
; #define PG8_SCHED __builtin_amdgcn_sched_barrier(0)
; template <class Epi, class Sched, bool ALIGN_EPI = false, bool SP2 = false>
; __device__ __forceinline__ void gemm_phase(PG8_LAS unsigned char* lds, const Gemm g, const Sched& S, const Epi& E) {
;     ...
;         for (int t = 0; t < nt; t += 2) {
;             const bool last = (t == nt - 2);
;             const char* a1 = cA + (g.gstrA ? (size_t)(t >> 2) * g.gstrA + (size_t)(t & 3) * kstep : (size_t)t * kstep) + kstep;
;             const char* a2 = last ? nA : cA + (g.gstrA ? (size_t)((t + 2) >> 2) * g.gstrA + (size_t)((t + 2) & 3) * kstep : (size_t)(t + 2) * kstep); const char* b2 = last ? nB : cB + (size_t)(t + 2) * kstep;
;             const char* a3 = a2 + kstep; const char* b3 = b2 + kstep;
;             if (last && has_next) S.a_ready(nxt);
;             if constexpr (Epi::HAS_PREFETCH) { if (t == nt - 4) E.prefetch(cur, tid, wid); }
;             if constexpr (SP2) {
;             PG8_LDB(B0, 0, 0); PG8_LDB(B1, 0, 1); PG8_SCHED; PG8_LDA(At, 0, 0); PG8_STAGE(PG8_SA(1, 1), a1 + hstepA, voffA);
;             PG8_WAIT_V(8); PG8_WAIT_L(0); PG8_BAR; PG8_MMA(0, 0, At, B0); PG8_MMA(0, 1, At, B1); PG8_BAR; PG8_SCHED;
;             PG8_LDA(At, 0, 1); PG8_STAGE(PG8_SB(0, 0), b2, voffB); PG8_STAGE(PG8_SB(0, 1), b2 + hstep, voffB); PG8_STAGE(PG8_SA(0, 0), a2, voffA);
;             PG8_WAIT_V(8); PG8_WAIT_L(0); PG8_BAR; PG8_MMA(1, 0, At, B0); PG8_MMA(1, 1, At, B1); PG8_BAR; PG8_SCHED;
.LBB0_53:
	s_add_u32 s14, s82, 0xfffc0080
	s_addc_u32 s15, s83, -1
	s_add_i32 s38, 0, 0x10000
	s_cmp_eq_u32 s52, 12
	s_cselect_b32 s15, s18, s15
	s_cselect_b32 s14, s24, s14
	s_cselect_b32 s41, s26, s36
	s_cselect_b32 s40, s30, s34
	s_add_i32 s56, 0, 0x14000
	v_add_u32_e32 v44, s38, v174
	v_add_u32_e32 v157, s56, v174
	ds_read_b128 v[24:27], v44
	ds_read_b128 v[28:31], v44 offset:1024
	ds_read_b128 v[40:43], v44 offset:2048
	ds_read_b128 v[44:47], v44 offset:3072
	ds_read_b128 v[186:189], v157
	ds_read_b128 v[190:193], v157 offset:1024
	ds_read_b128 v[194:197], v157 offset:2048
	ds_read_b128 v[198:201], v157 offset:3072
	v_lshl_add_u64 v[170:171], s[82:83], 0, v[152:153]
	s_add_i32 m0, s3, 0xc000
	ds_read_b128 v[202:205], v184
	ds_read_b128 v[206:209], v184 offset:1024
	ds_read_b128 v[214:217], v184 offset:2048
	ds_read_b128 v[218:221], v184 offset:3072
	ds_read_b128 v[222:225], v184 offset:4096
	ds_read_b128 v[240:243], v184 offset:5120
	ds_read_b128 v[244:247], v184 offset:6144
	ds_read_b128 v[248:251], v184 offset:7168
	global_load_lds_dwordx4 v[170:171], off
	v_lshl_add_u64 v[170:171], s[82:83], 0, v[154:155]
	s_add_i32 m0, s3, 0xe000
	s_nop 0
	global_load_lds_dwordx4 v[170:171], off
	s_waitcnt vmcnt(8)
	s_waitcnt lgkmcnt(0)
	s_barrier
	s_setprio 1
	s_waitcnt lgkmcnt(0)
	v_mfma_f32_16x16x32_bf16 v[140:143], v[24:27], v[202:205], v[140:143]
	v_mfma_f32_16x16x32_bf16 v[136:139], v[40:43], v[202:205], v[136:139]
	v_mfma_f32_16x16x32_bf16 v[124:127], v[24:27], v[214:217], v[124:127]
	v_mfma_f32_16x16x32_bf16 v[120:123], v[40:43], v[214:217], v[120:123]
	v_mfma_f32_16x16x32_bf16 v[108:111], v[24:27], v[222:225], v[108:111]
	v_mfma_f32_16x16x32_bf16 v[104:107], v[40:43], v[222:225], v[104:107]
	v_mfma_f32_16x16x32_bf16 v[92:95], v[24:27], v[244:247], v[92:95]
	v_mfma_f32_16x16x32_bf16 v[88:91], v[40:43], v[244:247], v[88:91]
	v_mfma_f32_16x16x32_bf16 v[140:143], v[28:31], v[206:209], v[140:143]
	v_mfma_f32_16x16x32_bf16 v[136:139], v[44:47], v[206:209], v[136:139]
	v_mfma_f32_16x16x32_bf16 v[124:127], v[28:31], v[218:221], v[124:127]
	v_mfma_f32_16x16x32_bf16 v[120:123], v[44:47], v[218:221], v[120:123]
	v_mfma_f32_16x16x32_bf16 v[108:111], v[28:31], v[240:243], v[108:111]
	v_mfma_f32_16x16x32_bf16 v[104:107], v[44:47], v[240:243], v[104:107]
	v_mfma_f32_16x16x32_bf16 v[92:95], v[28:31], v[248:251], v[92:95]
	v_mfma_f32_16x16x32_bf16 v[88:91], v[44:47], v[248:251], v[88:91]
	s_setprio 0
	s_setprio 1
	v_mfma_f32_16x16x32_bf16 v[132:135], v[186:189], v[202:205], v[132:135]
	v_mfma_f32_16x16x32_bf16 v[128:131], v[194:197], v[202:205], v[128:131]
	v_mfma_f32_16x16x32_bf16 v[116:119], v[186:189], v[214:217], v[116:119]
	v_mfma_f32_16x16x32_bf16 v[112:115], v[194:197], v[214:217], v[112:115]
	v_mfma_f32_16x16x32_bf16 v[100:103], v[186:189], v[222:225], v[100:103]
	v_mfma_f32_16x16x32_bf16 v[96:99], v[194:197], v[222:225], v[96:99]
	v_mfma_f32_16x16x32_bf16 v[84:87], v[186:189], v[244:247], v[84:87]
	v_mfma_f32_16x16x32_bf16 v[80:83], v[194:197], v[244:247], v[80:83]
	v_mfma_f32_16x16x32_bf16 v[132:135], v[190:193], v[206:209], v[132:135]
	v_mfma_f32_16x16x32_bf16 v[128:131], v[198:201], v[206:209], v[128:131]
	v_mfma_f32_16x16x32_bf16 v[116:119], v[190:193], v[218:221], v[116:119]
	v_mfma_f32_16x16x32_bf16 v[112:115], v[198:201], v[218:221], v[112:115]
	v_mfma_f32_16x16x32_bf16 v[100:103], v[190:193], v[240:243], v[100:103]
	v_mfma_f32_16x16x32_bf16 v[96:99], v[198:201], v[240:243], v[96:99]
	v_mfma_f32_16x16x32_bf16 v[84:87], v[190:193], v[248:251], v[84:87]
	s_barrier
	v_mfma_f32_16x16x32_bf16 v[80:83], v[198:201], v[248:251], v[80:83]
	s_setprio 0
	s_add_i32 s38, s38, s2
	v_lshl_add_u64 v[170:171], s[40:41], 0, v[146:147]
	s_mov_b32 m0, s38
	ds_read_b128 v[202:205], v184 offset:16384
	ds_read_b128 v[206:209], v184 offset:17408
	ds_read_b128 v[214:217], v184 offset:18432
	ds_read_b128 v[218:221], v184 offset:19456
	ds_read_b128 v[222:225], v184 offset:20480
	ds_read_b128 v[240:243], v184 offset:21504
	ds_read_b128 v[244:247], v184 offset:22528
	ds_read_b128 v[248:251], v184 offset:23552
	global_load_lds_dwordx4 v[170:171], off
	s_add_i32 m0, s38, 0x2000
	s_add_u32 s54, s40, 0x40000
	v_lshl_add_u64 v[210:211], s[40:41], 0, v[150:151]
	s_addc_u32 s55, s41, 0
	s_add_i32 s38, s56, s2
	global_load_lds_dwordx4 v[210:211], off
	v_lshl_add_u64 v[252:253], s[54:55], 0, v[146:147]
	s_mov_b32 m0, s38
	v_lshl_add_u64 v[234:235], s[14:15], 0, v[148:149]
	global_load_lds_dwordx4 v[252:253], off
	v_lshl_add_u64 v[252:253], s[54:55], 0, v[150:151]
	s_add_i32 m0, s38, 0x2000
	s_nop 0
	global_load_lds_dwordx4 v[252:253], off
	v_lshl_add_u64 v[252:253], s[14:15], 0, v[144:145]
	s_mov_b32 m0, s3
	s_nop 0
	global_load_lds_dwordx4 v[252:253], off
	s_mov_b32 m0, s16
	s_nop 0
	global_load_lds_dwordx4 v[234:235], off
	s_waitcnt vmcnt(8)
	s_waitcnt lgkmcnt(0)
	s_barrier
; #define PG8_STAGE(bufoff, gbase, voff) do { _Pragma("unroll") for (int _i = 0; _i < 2; ++_i) \
;         __builtin_amdgcn_global_load_lds((const unsigned*)((const char*)(gbase) + (voff)[_i]), (PG8_LAS unsigned*)(lds + (bufoff) + ldsw + _i * 8192), 16, 0, 0); } while (0)
; #define PG8_LDA(dst, b, h) do { _Pragma("unroll") for (int m = 0; m < 4; ++m) _Pragma("unroll") for (int k = 0; k < 2; ++k) dst[m][k] = *(const PG8_LAS bf16x8*)(lds + PG8_SA(b, h) + aoff + m * 2048 + k * 1024); } while (0)
; #define PG8_LDB(dst, b, h) do { _Pragma("unroll") for (int n = 0; n < 2; ++n) _Pragma("unroll") for (int k = 0; k < 2; ++k) dst[n][k] = *(const PG8_LAS bf16x8*)(lds + PG8_SB(b, h) + boff + n * 2048 + k * 1024); } while (0)
; #define PG8_MMA(ai, bj, At, Bt) do { __builtin_amdgcn_s_setprio(1); _Pragma("unroll") for (int m = 0; m < 4; ++m) _Pragma("unroll") for (int n = 0; n < 2; ++n) _Pragma("unroll") for (int k = 0; k < 2; ++k) \
;         acc[ai][bj][m][n] = __builtin_amdgcn_mfma_f32_16x16x32_bf16(Bt[n][k], At[m][k], acc[ai][bj][m][n], 0, 0, 0); __builtin_amdgcn_s_setprio(0); } while (0)
; #define PG8_WAIT_V(n) asm volatile("s_waitcnt vmcnt(" #n ")" ::: "memory")
; #define PG8_WAIT_L(n) asm volatile("s_waitcnt lgkmcnt(" #n ")" ::: "memory")
; #define PG8_BAR __builtin_amdgcn_s_barrier()
; #define PG8_SCHED __builtin_amdgcn_sched_barrier(0)
; template <class Epi, class Sched, bool ALIGN_EPI = false, bool SP2 = false>
; __device__ __forceinline__ void gemm_phase(PG8_LAS unsigned char* lds, const Gemm g, const Sched& S, const Epi& E) {
;     ...
;             PG8_LDA(At, 0, 1); PG8_STAGE(PG8_SB(0, 0), b2, voffB); PG8_STAGE(PG8_SB(0, 1), b2 + hstep, voffB); PG8_STAGE(PG8_SA(0, 0), a2, voffA);
;             PG8_WAIT_V(8); PG8_WAIT_L(0); PG8_BAR; PG8_MMA(1, 0, At, B0); PG8_MMA(1, 1, At, B1); PG8_BAR; PG8_SCHED;
;             PG8_LDB(B0, 1, 0); PG8_LDB(B1, 1, 1); PG8_SCHED; PG8_LDA(At, 1, 0); PG8_STAGE(PG8_SA(0, 1), a2 + hstepA, voffA);
;             PG8_WAIT_V(8); PG8_WAIT_L(0); PG8_BAR; PG8_MMA(0, 0, At, B0); PG8_MMA(0, 1, At, B1); PG8_BAR; PG8_SCHED;
	s_setprio 1
	s_waitcnt lgkmcnt(0)
	v_mfma_f32_16x16x32_bf16 v[76:79], v[24:27], v[202:205], v[76:79]
	v_mfma_f32_16x16x32_bf16 v[72:75], v[40:43], v[202:205], v[72:75]
	v_mfma_f32_16x16x32_bf16 v[60:63], v[24:27], v[214:217], v[60:63]
	v_mfma_f32_16x16x32_bf16 v[56:59], v[40:43], v[214:217], v[56:59]
	v_mfma_f32_16x16x32_bf16 v[36:39], v[24:27], v[222:225], v[36:39]
	v_mfma_f32_16x16x32_bf16 v[32:35], v[40:43], v[222:225], v[32:35]
	v_mfma_f32_16x16x32_bf16 v[12:15], v[24:27], v[244:247], v[12:15]
	v_mfma_f32_16x16x32_bf16 v[8:11], v[40:43], v[244:247], v[8:11]
	v_mfma_f32_16x16x32_bf16 v[76:79], v[28:31], v[206:209], v[76:79]
	v_mfma_f32_16x16x32_bf16 v[72:75], v[44:47], v[206:209], v[72:75]
	v_mfma_f32_16x16x32_bf16 v[60:63], v[28:31], v[218:221], v[60:63]
	v_mfma_f32_16x16x32_bf16 v[56:59], v[44:47], v[218:221], v[56:59]
	v_mfma_f32_16x16x32_bf16 v[36:39], v[28:31], v[240:243], v[36:39]
	v_mfma_f32_16x16x32_bf16 v[32:35], v[44:47], v[240:243], v[32:35]
	v_mfma_f32_16x16x32_bf16 v[12:15], v[28:31], v[248:251], v[12:15]
	v_mfma_f32_16x16x32_bf16 v[8:11], v[44:47], v[248:251], v[8:11]
	s_setprio 0
	s_setprio 1
	v_mfma_f32_16x16x32_bf16 v[20:23], v[186:189], v[222:225], v[20:23]
	v_mfma_f32_16x16x32_bf16 v[16:19], v[194:197], v[222:225], v[16:19]
	v_mfma_f32_16x16x32_bf16 v[4:7], v[186:189], v[244:247], v[4:7]
	v_mfma_f32_16x16x32_bf16 v[0:3], v[194:197], v[244:247], v[0:3]
	v_mfma_f32_16x16x32_bf16 v[24:27], v[186:189], v[202:205], v[68:71]
	v_mfma_f32_16x16x32_bf16 v[28:31], v[194:197], v[202:205], v[64:67]
	v_mfma_f32_16x16x32_bf16 v[40:43], v[186:189], v[214:217], v[52:55]
	v_mfma_f32_16x16x32_bf16 v[44:47], v[194:197], v[214:217], v[48:51]
	v_mfma_f32_16x16x32_bf16 v[20:23], v[190:193], v[240:243], v[20:23]
	v_mfma_f32_16x16x32_bf16 v[16:19], v[198:201], v[240:243], v[16:19]
	v_mfma_f32_16x16x32_bf16 v[4:7], v[190:193], v[248:251], v[4:7]
	v_mfma_f32_16x16x32_bf16 v[0:3], v[198:201], v[248:251], v[0:3]
	v_mfma_f32_16x16x32_bf16 v[24:27], v[190:193], v[206:209], v[24:27]
	v_mfma_f32_16x16x32_bf16 v[28:31], v[198:201], v[206:209], v[28:31]
	v_mfma_f32_16x16x32_bf16 v[40:43], v[190:193], v[218:221], v[40:43]
	s_barrier
	v_mfma_f32_16x16x32_bf16 v[44:47], v[198:201], v[218:221], v[44:47]
	s_setprio 0
	s_add_i32 s38, 0, 0x18000
	s_add_i32 s54, 0, 0x1c000
	v_add_u32_e32 v68, s38, v174
	v_add_u32_e32 v157, s54, v174
	ds_read_b128 v[48:51], v68
	ds_read_b128 v[52:55], v68 offset:1024
	ds_read_b128 v[64:67], v68 offset:2048
	ds_read_b128 v[68:71], v68 offset:3072
	ds_read_b128 v[186:189], v157
	ds_read_b128 v[190:193], v157 offset:1024
	ds_read_b128 v[194:197], v157 offset:2048
	ds_read_b128 v[198:201], v157 offset:3072
	s_add_u32 s14, s14, 0x40000
	s_addc_u32 s15, s15, 0
	s_mov_b32 m0, s17
	v_lshl_add_u64 v[176:177], s[14:15], 0, v[144:145]
	ds_read_b128 v[202:205], v184 offset:32768
	ds_read_b128 v[206:209], v184 offset:33792
	ds_read_b128 v[214:217], v184 offset:34816
	ds_read_b128 v[218:221], v184 offset:35840
	ds_read_b128 v[222:225], v184 offset:36864
	ds_read_b128 v[240:243], v184 offset:37888
	ds_read_b128 v[244:247], v184 offset:38912
	ds_read_b128 v[248:251], v184 offset:39936
	global_load_lds_dwordx4 v[176:177], off
	v_lshl_add_u64 v[176:177], s[14:15], 0, v[148:149]
	s_mov_b32 m0, s20
	s_nop 0
	global_load_lds_dwordx4 v[176:177], off
	s_waitcnt vmcnt(8)
	s_waitcnt lgkmcnt(0)
	s_barrier
	s_setprio 1
	s_waitcnt lgkmcnt(0)
	v_mfma_f32_16x16x32_bf16 v[140:143], v[48:51], v[202:205], v[140:143]
	v_mfma_f32_16x16x32_bf16 v[136:139], v[64:67], v[202:205], v[136:139]
	v_mfma_f32_16x16x32_bf16 v[124:127], v[48:51], v[214:217], v[124:127]
	v_mfma_f32_16x16x32_bf16 v[120:123], v[64:67], v[214:217], v[120:123]
	v_mfma_f32_16x16x32_bf16 v[108:111], v[48:51], v[222:225], v[108:111]
	v_mfma_f32_16x16x32_bf16 v[104:107], v[64:67], v[222:225], v[104:107]
	v_mfma_f32_16x16x32_bf16 v[92:95], v[48:51], v[244:247], v[92:95]
	v_mfma_f32_16x16x32_bf16 v[88:91], v[64:67], v[244:247], v[88:91]
	v_mfma_f32_16x16x32_bf16 v[140:143], v[52:55], v[206:209], v[140:143]
	v_mfma_f32_16x16x32_bf16 v[136:139], v[68:71], v[206:209], v[136:139]
	v_mfma_f32_16x16x32_bf16 v[124:127], v[52:55], v[218:221], v[124:127]
	v_mfma_f32_16x16x32_bf16 v[120:123], v[68:71], v[218:221], v[120:123]
	v_mfma_f32_16x16x32_bf16 v[108:111], v[52:55], v[240:243], v[108:111]
	v_mfma_f32_16x16x32_bf16 v[104:107], v[68:71], v[240:243], v[104:107]
	v_mfma_f32_16x16x32_bf16 v[92:95], v[52:55], v[248:251], v[92:95]
	v_mfma_f32_16x16x32_bf16 v[88:91], v[68:71], v[248:251], v[88:91]
	s_setprio 0
	s_setprio 1
	v_mfma_f32_16x16x32_bf16 v[132:135], v[186:189], v[202:205], v[132:135]
	v_mfma_f32_16x16x32_bf16 v[128:131], v[194:197], v[202:205], v[128:131]
	v_mfma_f32_16x16x32_bf16 v[116:119], v[186:189], v[214:217], v[116:119]
	v_mfma_f32_16x16x32_bf16 v[112:115], v[194:197], v[214:217], v[112:115]
	v_mfma_f32_16x16x32_bf16 v[100:103], v[186:189], v[222:225], v[100:103]
	v_mfma_f32_16x16x32_bf16 v[96:99], v[194:197], v[222:225], v[96:99]
	v_mfma_f32_16x16x32_bf16 v[84:87], v[186:189], v[244:247], v[84:87]
	v_mfma_f32_16x16x32_bf16 v[80:83], v[194:197], v[244:247], v[80:83]
	v_mfma_f32_16x16x32_bf16 v[132:135], v[190:193], v[206:209], v[132:135]
	v_mfma_f32_16x16x32_bf16 v[128:131], v[198:201], v[206:209], v[128:131]
	v_mfma_f32_16x16x32_bf16 v[116:119], v[190:193], v[218:221], v[116:119]
	v_mfma_f32_16x16x32_bf16 v[112:115], v[198:201], v[218:221], v[112:115]
	v_mfma_f32_16x16x32_bf16 v[100:103], v[190:193], v[240:243], v[100:103]
	v_mfma_f32_16x16x32_bf16 v[96:99], v[198:201], v[240:243], v[96:99]
	v_mfma_f32_16x16x32_bf16 v[84:87], v[190:193], v[248:251], v[84:87]
	s_barrier
; #define PG8_STAGE(bufoff, gbase, voff) do { _Pragma("unroll") for (int _i = 0; _i < 2; ++_i) \
;         __builtin_amdgcn_global_load_lds((const unsigned*)((const char*)(gbase) + (voff)[_i]), (PG8_LAS unsigned*)(lds + (bufoff) + ldsw + _i * 8192), 16, 0, 0); } while (0)
; #define PG8_LDA(dst, b, h) do { _Pragma("unroll") for (int m = 0; m < 4; ++m) _Pragma("unroll") for (int k = 0; k < 2; ++k) dst[m][k] = *(const PG8_LAS bf16x8*)(lds + PG8_SA(b, h) + aoff + m * 2048 + k * 1024); } while (0)
; #define PG8_LDB(dst, b, h) do { _Pragma("unroll") for (int n = 0; n < 2; ++n) _Pragma("unroll") for (int k = 0; k < 2; ++k) dst[n][k] = *(const PG8_LAS bf16x8*)(lds + PG8_SB(b, h) + boff + n * 2048 + k * 1024); } while (0)
; #define PG8_MMA(ai, bj, At, Bt) do { __builtin_amdgcn_s_setprio(1); _Pragma("unroll") for (int m = 0; m < 4; ++m) _Pragma("unroll") for (int n = 0; n < 2; ++n) _Pragma("unroll") for (int k = 0; k < 2; ++k) \
;         acc[ai][bj][m][n] = __builtin_amdgcn_mfma_f32_16x16x32_bf16(Bt[n][k], At[m][k], acc[ai][bj][m][n], 0, 0, 0); __builtin_amdgcn_s_setprio(0); } while (0)
; #define PG8_WAIT_V(n) asm volatile("s_waitcnt vmcnt(" #n ")" ::: "memory")
; #define PG8_WAIT_L(n) asm volatile("s_waitcnt lgkmcnt(" #n ")" ::: "memory")
; #define PG8_BAR __builtin_amdgcn_s_barrier()
; #define PG8_SCHED __builtin_amdgcn_sched_barrier(0)
; template <class Epi, class Sched, bool ALIGN_EPI = false, bool SP2 = false>
; __device__ __forceinline__ void gemm_phase(PG8_LAS unsigned char* lds, const Gemm g, const Sched& S, const Epi& E) {
;     ...
;             PG8_LDB(B0, 1, 0); PG8_LDB(B1, 1, 1); PG8_SCHED; PG8_LDA(At, 1, 0); PG8_STAGE(PG8_SA(0, 1), a2 + hstepA, voffA);
;             PG8_WAIT_V(8); PG8_WAIT_L(0); PG8_BAR; PG8_MMA(0, 0, At, B0); PG8_MMA(0, 1, At, B1); PG8_BAR; PG8_SCHED;
;             PG8_LDA(At, 1, 1); PG8_STAGE(PG8_SB(1, 0), b3, voffB); PG8_STAGE(PG8_SB(1, 1), b3 + hstep, voffB); PG8_STAGE(PG8_SA(1, 0), a3, voffA);
;             PG8_WAIT_V(8); PG8_WAIT_L(0); PG8_BAR; PG8_MMA(1, 0, At, B0); PG8_MMA(1, 1, At, B1); PG8_BAR; PG8_SCHED;
	v_mfma_f32_16x16x32_bf16 v[80:83], v[198:201], v[248:251], v[80:83]
	s_setprio 0
	s_add_i32 s14, s38, s2
	v_lshl_add_u64 v[170:171], v[170:171], 0, s[22:23]
	s_mov_b32 m0, s14
	ds_read_b128 v[202:205], v184 offset:49152
	ds_read_b128 v[206:209], v184 offset:50176
	ds_read_b128 v[214:217], v184 offset:51200
	ds_read_b128 v[218:221], v184 offset:52224
	ds_read_b128 v[222:225], v184 offset:53248
	ds_read_b128 v[240:243], v184 offset:54272
	ds_read_b128 v[244:247], v184 offset:55296
	ds_read_b128 v[248:251], v184 offset:56320
	global_load_lds_dwordx4 v[170:171], off
	s_add_i32 m0, s14, 0x2000
	s_add_u32 s14, s40, 0x40080
	v_lshl_add_u64 v[170:171], v[210:211], 0, s[22:23]
	s_addc_u32 s15, s41, 0
	s_add_i32 s38, s54, s2
	global_load_lds_dwordx4 v[170:171], off
	v_lshl_add_u64 v[170:171], s[14:15], 0, v[146:147]
	s_mov_b32 m0, s38
	s_nop 0
	global_load_lds_dwordx4 v[170:171], off
	v_lshl_add_u64 v[170:171], s[14:15], 0, v[150:151]
	s_add_i32 m0, s38, 0x2000
	s_nop 0
	global_load_lds_dwordx4 v[170:171], off
	v_lshl_add_u64 v[170:171], v[252:253], 0, s[22:23]
	s_mov_b32 m0, s29
	s_nop 0
	global_load_lds_dwordx4 v[170:171], off
	v_lshl_add_u64 v[170:171], v[234:235], 0, s[22:23]
	s_mov_b32 m0, s31
	s_nop 0
	global_load_lds_dwordx4 v[170:171], off
	s_waitcnt vmcnt(8)
	s_waitcnt lgkmcnt(0)
	s_barrier
	s_setprio 1
	s_waitcnt lgkmcnt(0)
	v_mfma_f32_16x16x32_bf16 v[76:79], v[48:51], v[202:205], v[76:79]
	v_mfma_f32_16x16x32_bf16 v[72:75], v[64:67], v[202:205], v[72:75]
	v_mfma_f32_16x16x32_bf16 v[60:63], v[48:51], v[214:217], v[60:63]
	v_mfma_f32_16x16x32_bf16 v[56:59], v[64:67], v[214:217], v[56:59]
	v_mfma_f32_16x16x32_bf16 v[36:39], v[48:51], v[222:225], v[36:39]
	v_mfma_f32_16x16x32_bf16 v[32:35], v[64:67], v[222:225], v[32:35]
	v_mfma_f32_16x16x32_bf16 v[12:15], v[48:51], v[244:247], v[12:15]
	v_mfma_f32_16x16x32_bf16 v[8:11], v[64:67], v[244:247], v[8:11]
	v_mfma_f32_16x16x32_bf16 v[76:79], v[52:55], v[206:209], v[76:79]
	v_mfma_f32_16x16x32_bf16 v[72:75], v[68:71], v[206:209], v[72:75]
	v_mfma_f32_16x16x32_bf16 v[60:63], v[52:55], v[218:221], v[60:63]
	v_mfma_f32_16x16x32_bf16 v[56:59], v[68:71], v[218:221], v[56:59]
	v_mfma_f32_16x16x32_bf16 v[36:39], v[52:55], v[240:243], v[36:39]
	v_mfma_f32_16x16x32_bf16 v[32:35], v[68:71], v[240:243], v[32:35]
	v_mfma_f32_16x16x32_bf16 v[12:15], v[52:55], v[248:251], v[12:15]
	v_mfma_f32_16x16x32_bf16 v[8:11], v[68:71], v[248:251], v[8:11]
	s_setprio 0
	s_setprio 1
	v_mfma_f32_16x16x32_bf16 v[24:27], v[186:189], v[202:205], v[24:27]
	v_mfma_f32_16x16x32_bf16 v[68:71], v[190:193], v[206:209], v[24:27]
	v_mfma_f32_16x16x32_bf16 v[24:27], v[194:197], v[202:205], v[28:31]
	v_mfma_f32_16x16x32_bf16 v[64:67], v[198:201], v[206:209], v[24:27]
	v_mfma_f32_16x16x32_bf16 v[24:27], v[186:189], v[214:217], v[40:43]
	v_mfma_f32_16x16x32_bf16 v[52:55], v[190:193], v[218:221], v[24:27]
	v_mfma_f32_16x16x32_bf16 v[24:27], v[194:197], v[214:217], v[44:47]
	v_mfma_f32_16x16x32_bf16 v[20:23], v[186:189], v[222:225], v[20:23]
	v_mfma_f32_16x16x32_bf16 v[16:19], v[194:197], v[222:225], v[16:19]
	v_mfma_f32_16x16x32_bf16 v[4:7], v[186:189], v[244:247], v[4:7]
	v_mfma_f32_16x16x32_bf16 v[0:3], v[194:197], v[244:247], v[0:3]
	v_mfma_f32_16x16x32_bf16 v[48:51], v[198:201], v[218:221], v[24:27]
	v_mfma_f32_16x16x32_bf16 v[20:23], v[190:193], v[240:243], v[20:23]
	v_mfma_f32_16x16x32_bf16 v[16:19], v[198:201], v[240:243], v[16:19]
	v_mfma_f32_16x16x32_bf16 v[4:7], v[190:193], v[248:251], v[4:7]
	s_barrier
	v_mfma_f32_16x16x32_bf16 v[0:3], v[198:201], v[248:251], v[0:3]
	s_setprio 0
	s_nop 7
	s_add_i32 s52, s52, 2
	s_add_u32 s82, s82, 0x100
	s_addc_u32 s83, s83, 0
	s_add_u32 s34, s34, 0x100
	s_addc_u32 s36, s36, 0
	s_cmp_gt_u32 s52, 13
	s_cbranch_scc0 .LBB0_53
	s_and_b64 vcc, exec, s[72:73]
	s_cbranch_vccz .LBB0_56
	s_barrier

; #define PG8_STAGE(bufoff, gbase, voff) do { _Pragma("unroll") for (int _i = 0; _i < 2; ++_i) \
;         __builtin_amdgcn_global_load_lds((const unsigned*)((const char*)(gbase) + (voff)[_i]), (PG8_LAS unsigned*)(lds + (bufoff) + ldsw + _i * 8192), 16, 0, 0); } while (0)
; #define PG8_LDA(dst, b, h) do { _Pragma("unroll") for (int m = 0; m < 4; ++m) _Pragma("unroll") for (int k = 0; k < 2; ++k) dst[m][k] = *(const PG8_LAS bf16x8*)(lds + PG8_SA(b, h) + aoff + m * 2048 + k * 1024); } while (0)
; #define PG8_LDB(dst, b, h) do { _Pragma("unroll") for (int n = 0; n < 2; ++n) _Pragma("unroll") for (int k = 0; k < 2; ++k) dst[n][k] = *(const PG8_LAS bf16x8*)(lds + PG8_SB(b, h) + boff + n * 2048 + k * 1024); } while (0)
; #define PG8_WAIT_V(n) asm volatile("s_waitcnt vmcnt(" #n ")" ::: "memory")
; #define PG8_WAIT_L(n) asm volatile("s_waitcnt lgkmcnt(" #n ")" ::: "memory")
; #define PG8_BAR __builtin_amdgcn_s_barrier()
; #define PG8_SCHED __builtin_amdgcn_sched_barrier(0)
; template <class Epi, class Sched, bool ALIGN_EPI = false, bool SP2 = false>
; __device__ __forceinline__ void gemm_phase(PG8_LAS unsigned char* lds, const Gemm g, const Sched& S, const Epi& E) {
;     ...
;         for (int t = 0; t < nt; t += 2) {
;             const bool last = (t == nt - 2);
;             const char* a1 = cA + (g.gstrA ? (size_t)(t >> 2) * g.gstrA + (size_t)(t & 3) * kstep : (size_t)t * kstep) + kstep;
;             const char* a2 = last ? nA : cA + (g.gstrA ? (size_t)((t + 2) >> 2) * g.gstrA + (size_t)((t + 2) & 3) * kstep : (size_t)(t + 2) * kstep); const char* b2 = last ? nB : cB + (size_t)(t + 2) * kstep;
;             const char* a3 = a2 + kstep; const char* b3 = b2 + kstep;
;             if (last && has_next) S.a_ready(nxt);
;             if constexpr (Epi::HAS_PREFETCH) { if (t == nt - 4) E.prefetch(cur, tid, wid); }
;             if constexpr (SP2) {
;             PG8_LDB(B0, 0, 0); PG8_LDB(B1, 0, 1); PG8_SCHED; PG8_LDA(At, 0, 0); PG8_STAGE(PG8_SA(1, 1), a1 + hstepA, voffA);
;             PG8_WAIT_V(8); PG8_WAIT_L(0); PG8_BAR; PG8_MMA(0, 0, At, B0); PG8_MMA(0, 1, At, B1); PG8_BAR; PG8_SCHED;
;             PG8_LDA(At, 0, 1); PG8_STAGE(PG8_SB(0, 0), b2, voffB); PG8_STAGE(PG8_SB(0, 1), b2 + hstep, voffB); PG8_STAGE(PG8_SA(0, 0), a2, voffA);
;             PG8_WAIT_V(8); PG8_WAIT_L(0); PG8_BAR; PG8_MMA(1, 0, At, B0); PG8_MMA(1, 1, At, B1); PG8_BAR; PG8_SCHED;
.LBB0_119:
	s_add_u32 s14, s74, 0xfffc0080
	s_addc_u32 s15, s75, -1
	s_add_i32 s35, 0, 0x10000
	s_cmp_eq_u32 s34, 12
	s_cselect_b32 s15, s24, s15
	s_cselect_b32 s14, s26, s14
	s_cselect_b32 s41, s28, s31
	s_cselect_b32 s40, s29, s30
	s_add_i32 s38, 0, 0x14000
	v_add_u32_e32 v76, s35, v157
	v_add_u32_e32 v154, s38, v157
	ds_read_b128 v[60:63], v76
	ds_read_b128 v[68:71], v76 offset:1024
	ds_read_b128 v[72:75], v76 offset:2048
	ds_read_b128 v[76:79], v76 offset:3072
	ds_read_b128 v[170:173], v154
	ds_read_b128 v[174:177], v154 offset:1024
	ds_read_b128 v[178:181], v154 offset:2048
	ds_read_b128 v[182:185], v154 offset:3072
	v_lshl_add_u64 v[154:155], s[74:75], 0, v[150:151]
	s_add_i32 m0, s3, 0xc000
	ds_read_b128 v[186:189], v168
	ds_read_b128 v[190:193], v168 offset:1024
	ds_read_b128 v[194:197], v168 offset:2048
	ds_read_b128 v[198:201], v168 offset:3072
	ds_read_b128 v[202:205], v168 offset:4096
	ds_read_b128 v[206:209], v168 offset:5120
	ds_read_b128 v[214:217], v168 offset:6144
	ds_read_b128 v[218:221], v168 offset:7168
	global_load_lds_dwordx4 v[154:155], off
	v_lshl_add_u64 v[154:155], s[74:75], 0, v[152:153]
	s_add_i32 m0, s3, 0xe000
	s_nop 0
	global_load_lds_dwordx4 v[154:155], off
	s_waitcnt vmcnt(8)
	s_waitcnt lgkmcnt(0)
	s_barrier
	s_setprio 1
	s_waitcnt lgkmcnt(0)
	v_mfma_f32_16x16x32_bf16 v[140:143], v[60:63], v[186:189], v[140:143]
	v_mfma_f32_16x16x32_bf16 v[136:139], v[72:75], v[186:189], v[136:139]
	v_mfma_f32_16x16x32_bf16 v[124:127], v[60:63], v[194:197], v[124:127]
	v_mfma_f32_16x16x32_bf16 v[120:123], v[72:75], v[194:197], v[120:123]
	v_mfma_f32_16x16x32_bf16 v[108:111], v[60:63], v[202:205], v[108:111]
	v_mfma_f32_16x16x32_bf16 v[104:107], v[72:75], v[202:205], v[104:107]
	v_mfma_f32_16x16x32_bf16 v[92:95], v[60:63], v[214:217], v[92:95]
	v_mfma_f32_16x16x32_bf16 v[88:91], v[72:75], v[214:217], v[88:91]
	v_mfma_f32_16x16x32_bf16 v[140:143], v[68:71], v[190:193], v[140:143]
	v_mfma_f32_16x16x32_bf16 v[136:139], v[76:79], v[190:193], v[136:139]
	v_mfma_f32_16x16x32_bf16 v[124:127], v[68:71], v[198:201], v[124:127]
	v_mfma_f32_16x16x32_bf16 v[120:123], v[76:79], v[198:201], v[120:123]
	v_mfma_f32_16x16x32_bf16 v[108:111], v[68:71], v[206:209], v[108:111]
	v_mfma_f32_16x16x32_bf16 v[104:107], v[76:79], v[206:209], v[104:107]
	v_mfma_f32_16x16x32_bf16 v[92:95], v[68:71], v[218:221], v[92:95]
	v_mfma_f32_16x16x32_bf16 v[88:91], v[76:79], v[218:221], v[88:91]
	s_setprio 0
	s_setprio 1
	v_mfma_f32_16x16x32_bf16 v[132:135], v[170:173], v[186:189], v[132:135]
	v_mfma_f32_16x16x32_bf16 v[128:131], v[178:181], v[186:189], v[128:131]
	v_mfma_f32_16x16x32_bf16 v[116:119], v[170:173], v[194:197], v[116:119]
	v_mfma_f32_16x16x32_bf16 v[112:115], v[178:181], v[194:197], v[112:115]
	v_mfma_f32_16x16x32_bf16 v[100:103], v[170:173], v[202:205], v[100:103]
	v_mfma_f32_16x16x32_bf16 v[96:99], v[178:181], v[202:205], v[96:99]
	v_mfma_f32_16x16x32_bf16 v[84:87], v[170:173], v[214:217], v[84:87]
	v_mfma_f32_16x16x32_bf16 v[80:83], v[178:181], v[214:217], v[80:83]
	v_mfma_f32_16x16x32_bf16 v[132:135], v[174:177], v[190:193], v[132:135]
	v_mfma_f32_16x16x32_bf16 v[128:131], v[182:185], v[190:193], v[128:131]
	v_mfma_f32_16x16x32_bf16 v[116:119], v[174:177], v[198:201], v[116:119]
	v_mfma_f32_16x16x32_bf16 v[112:115], v[182:185], v[198:201], v[112:115]
	v_mfma_f32_16x16x32_bf16 v[100:103], v[174:177], v[206:209], v[100:103]
	v_mfma_f32_16x16x32_bf16 v[96:99], v[182:185], v[206:209], v[96:99]
	v_mfma_f32_16x16x32_bf16 v[84:87], v[174:177], v[218:221], v[84:87]
	s_barrier
	v_mfma_f32_16x16x32_bf16 v[80:83], v[182:185], v[218:221], v[80:83]
	s_setprio 0
	s_add_i32 s35, s35, s0
	v_lshl_add_u64 v[154:155], s[40:41], 0, v[212:213]
	s_mov_b32 m0, s35
	ds_read_b128 v[186:189], v168 offset:16384
	ds_read_b128 v[190:193], v168 offset:17408
	ds_read_b128 v[194:197], v168 offset:18432
	ds_read_b128 v[198:201], v168 offset:19456
	ds_read_b128 v[202:205], v168 offset:20480
	ds_read_b128 v[206:209], v168 offset:21504
	ds_read_b128 v[214:217], v168 offset:22528
	ds_read_b128 v[218:221], v168 offset:23552
	global_load_lds_dwordx4 v[154:155], off
	s_add_i32 m0, s35, 0x2000
	s_add_u32 s36, s40, 0x40000
	v_lshl_add_u64 v[210:211], s[40:41], 0, v[148:149]
	s_addc_u32 s37, s41, 0
	s_add_i32 s35, s38, s0
	global_load_lds_dwordx4 v[210:211], off
	v_lshl_add_u64 v[222:223], s[36:37], 0, v[212:213]
	s_mov_b32 m0, s35
	v_lshl_add_u64 v[224:225], s[14:15], 0, v[146:147]
	global_load_lds_dwordx4 v[222:223], off
	v_lshl_add_u64 v[222:223], s[36:37], 0, v[148:149]
	s_add_i32 m0, s35, 0x2000
	s_nop 0
	global_load_lds_dwordx4 v[222:223], off
	v_lshl_add_u64 v[222:223], s[14:15], 0, v[144:145]
	s_mov_b32 m0, s3
	s_nop 0
	global_load_lds_dwordx4 v[222:223], off
	s_mov_b32 m0, s16
	s_nop 0
	global_load_lds_dwordx4 v[224:225], off
	s_waitcnt vmcnt(8)
	s_waitcnt lgkmcnt(0)
	s_barrier
; #define PG8_STAGE(bufoff, gbase, voff) do { _Pragma("unroll") for (int _i = 0; _i < 2; ++_i) \
;         __builtin_amdgcn_global_load_lds((const unsigned*)((const char*)(gbase) + (voff)[_i]), (PG8_LAS unsigned*)(lds + (bufoff) + ldsw + _i * 8192), 16, 0, 0); } while (0)
; #define PG8_LDA(dst, b, h) do { _Pragma("unroll") for (int m = 0; m < 4; ++m) _Pragma("unroll") for (int k = 0; k < 2; ++k) dst[m][k] = *(const PG8_LAS bf16x8*)(lds + PG8_SA(b, h) + aoff + m * 2048 + k * 1024); } while (0)
; #define PG8_LDB(dst, b, h) do { _Pragma("unroll") for (int n = 0; n < 2; ++n) _Pragma("unroll") for (int k = 0; k < 2; ++k) dst[n][k] = *(const PG8_LAS bf16x8*)(lds + PG8_SB(b, h) + boff + n * 2048 + k * 1024); } while (0)
; #define PG8_MMA(ai, bj, At, Bt) do { __builtin_amdgcn_s_setprio(1); _Pragma("unroll") for (int m = 0; m < 4; ++m) _Pragma("unroll") for (int n = 0; n < 2; ++n) _Pragma("unroll") for (int k = 0; k < 2; ++k) \
;         acc[ai][bj][m][n] = __builtin_amdgcn_mfma_f32_16x16x32_bf16(Bt[n][k], At[m][k], acc[ai][bj][m][n], 0, 0, 0); __builtin_amdgcn_s_setprio(0); } while (0)
; #define PG8_WAIT_V(n) asm volatile("s_waitcnt vmcnt(" #n ")" ::: "memory")
; #define PG8_WAIT_L(n) asm volatile("s_waitcnt lgkmcnt(" #n ")" ::: "memory")
; #define PG8_BAR __builtin_amdgcn_s_barrier()
; #define PG8_SCHED __builtin_amdgcn_sched_barrier(0)
; template <class Epi, class Sched, bool ALIGN_EPI = false, bool SP2 = false>
; __device__ __forceinline__ void gemm_phase(PG8_LAS unsigned char* lds, const Gemm g, const Sched& S, const Epi& E) {
;     ...
;             PG8_LDA(At, 0, 1); PG8_STAGE(PG8_SB(0, 0), b2, voffB); PG8_STAGE(PG8_SB(0, 1), b2 + hstep, voffB); PG8_STAGE(PG8_SA(0, 0), a2, voffA);
;             PG8_WAIT_V(8); PG8_WAIT_L(0); PG8_BAR; PG8_MMA(1, 0, At, B0); PG8_MMA(1, 1, At, B1); PG8_BAR; PG8_SCHED;
;             PG8_LDB(B0, 1, 0); PG8_LDB(B1, 1, 1); PG8_SCHED; PG8_LDA(At, 1, 0); PG8_STAGE(PG8_SA(0, 1), a2 + hstepA, voffA);
;             PG8_WAIT_V(8); PG8_WAIT_L(0); PG8_BAR; PG8_MMA(0, 0, At, B0); PG8_MMA(0, 1, At, B1); PG8_BAR; PG8_SCHED;
	s_setprio 1
	s_waitcnt lgkmcnt(0)
	v_mfma_f32_16x16x32_bf16 v[64:67], v[60:63], v[186:189], v[64:67]
	v_mfma_f32_16x16x32_bf16 v[56:59], v[72:75], v[186:189], v[56:59]
	v_mfma_f32_16x16x32_bf16 v[44:47], v[60:63], v[194:197], v[44:47]
	v_mfma_f32_16x16x32_bf16 v[40:43], v[72:75], v[194:197], v[40:43]
	v_mfma_f32_16x16x32_bf16 v[28:31], v[60:63], v[202:205], v[28:31]
	v_mfma_f32_16x16x32_bf16 v[24:27], v[72:75], v[202:205], v[24:27]
	v_mfma_f32_16x16x32_bf16 v[12:15], v[60:63], v[214:217], v[12:15]
	v_mfma_f32_16x16x32_bf16 v[8:11], v[72:75], v[214:217], v[8:11]
	v_mfma_f32_16x16x32_bf16 v[64:67], v[68:71], v[190:193], v[64:67]
	v_mfma_f32_16x16x32_bf16 v[56:59], v[76:79], v[190:193], v[56:59]
	v_mfma_f32_16x16x32_bf16 v[44:47], v[68:71], v[198:201], v[44:47]
	v_mfma_f32_16x16x32_bf16 v[40:43], v[76:79], v[198:201], v[40:43]
	v_mfma_f32_16x16x32_bf16 v[28:31], v[68:71], v[206:209], v[28:31]
	v_mfma_f32_16x16x32_bf16 v[24:27], v[76:79], v[206:209], v[24:27]
	v_mfma_f32_16x16x32_bf16 v[12:15], v[68:71], v[218:221], v[12:15]
	v_mfma_f32_16x16x32_bf16 v[8:11], v[76:79], v[218:221], v[8:11]
	s_setprio 0
	s_setprio 1
	v_mfma_f32_16x16x32_bf16 v[52:55], v[170:173], v[186:189], v[52:55]
	v_mfma_f32_16x16x32_bf16 v[48:51], v[178:181], v[186:189], v[48:51]
	v_mfma_f32_16x16x32_bf16 v[36:39], v[170:173], v[194:197], v[36:39]
	v_mfma_f32_16x16x32_bf16 v[32:35], v[178:181], v[194:197], v[32:35]
	v_mfma_f32_16x16x32_bf16 v[20:23], v[170:173], v[202:205], v[20:23]
	v_mfma_f32_16x16x32_bf16 v[16:19], v[178:181], v[202:205], v[16:19]
	v_mfma_f32_16x16x32_bf16 v[4:7], v[170:173], v[214:217], v[4:7]
	v_mfma_f32_16x16x32_bf16 v[0:3], v[178:181], v[214:217], v[0:3]
	v_mfma_f32_16x16x32_bf16 v[52:55], v[174:177], v[190:193], v[52:55]
	v_mfma_f32_16x16x32_bf16 v[48:51], v[182:185], v[190:193], v[48:51]
	v_mfma_f32_16x16x32_bf16 v[36:39], v[174:177], v[198:201], v[36:39]
	v_mfma_f32_16x16x32_bf16 v[32:35], v[182:185], v[198:201], v[32:35]
	v_mfma_f32_16x16x32_bf16 v[20:23], v[174:177], v[206:209], v[20:23]
	v_mfma_f32_16x16x32_bf16 v[16:19], v[182:185], v[206:209], v[16:19]
	v_mfma_f32_16x16x32_bf16 v[4:7], v[174:177], v[218:221], v[4:7]
	s_barrier
	v_mfma_f32_16x16x32_bf16 v[0:3], v[182:185], v[218:221], v[0:3]
	s_setprio 0
	s_add_i32 s35, 0, 0x18000
	s_add_i32 s36, 0, 0x1c000
	v_add_u32_e32 v76, s35, v157
	v_add_u32_e32 v169, s36, v157
	ds_read_b128 v[60:63], v76
	ds_read_b128 v[68:71], v76 offset:1024
	ds_read_b128 v[72:75], v76 offset:2048
	ds_read_b128 v[76:79], v76 offset:3072
	ds_read_b128 v[170:173], v169
	ds_read_b128 v[174:177], v169 offset:1024
	ds_read_b128 v[178:181], v169 offset:2048
	ds_read_b128 v[182:185], v169 offset:3072
	s_add_u32 s14, s14, 0x40000
	s_addc_u32 s15, s15, 0
	s_mov_b32 m0, s17
	v_lshl_add_u64 v[240:241], s[14:15], 0, v[144:145]
	ds_read_b128 v[186:189], v168 offset:32768
	ds_read_b128 v[190:193], v168 offset:33792
	ds_read_b128 v[194:197], v168 offset:34816
	ds_read_b128 v[198:201], v168 offset:35840
	ds_read_b128 v[202:205], v168 offset:36864
	ds_read_b128 v[206:209], v168 offset:37888
	ds_read_b128 v[214:217], v168 offset:38912
	ds_read_b128 v[218:221], v168 offset:39936
	global_load_lds_dwordx4 v[240:241], off
	v_lshl_add_u64 v[240:241], s[14:15], 0, v[146:147]
	s_mov_b32 m0, s18
	s_nop 0
	global_load_lds_dwordx4 v[240:241], off
	s_waitcnt vmcnt(8)
	s_waitcnt lgkmcnt(0)
	s_barrier
	s_setprio 1
	s_waitcnt lgkmcnt(0)
	v_mfma_f32_16x16x32_bf16 v[140:143], v[60:63], v[186:189], v[140:143]
	v_mfma_f32_16x16x32_bf16 v[136:139], v[72:75], v[186:189], v[136:139]
	v_mfma_f32_16x16x32_bf16 v[124:127], v[60:63], v[194:197], v[124:127]
	v_mfma_f32_16x16x32_bf16 v[120:123], v[72:75], v[194:197], v[120:123]
	v_mfma_f32_16x16x32_bf16 v[108:111], v[60:63], v[202:205], v[108:111]
	v_mfma_f32_16x16x32_bf16 v[104:107], v[72:75], v[202:205], v[104:107]
	v_mfma_f32_16x16x32_bf16 v[92:95], v[60:63], v[214:217], v[92:95]
	v_mfma_f32_16x16x32_bf16 v[88:91], v[72:75], v[214:217], v[88:91]
	v_mfma_f32_16x16x32_bf16 v[140:143], v[68:71], v[190:193], v[140:143]
	v_mfma_f32_16x16x32_bf16 v[136:139], v[76:79], v[190:193], v[136:139]
	v_mfma_f32_16x16x32_bf16 v[124:127], v[68:71], v[198:201], v[124:127]
	v_mfma_f32_16x16x32_bf16 v[120:123], v[76:79], v[198:201], v[120:123]
	v_mfma_f32_16x16x32_bf16 v[108:111], v[68:71], v[206:209], v[108:111]
	v_mfma_f32_16x16x32_bf16 v[104:107], v[76:79], v[206:209], v[104:107]
	v_mfma_f32_16x16x32_bf16 v[92:95], v[68:71], v[218:221], v[92:95]
	v_mfma_f32_16x16x32_bf16 v[88:91], v[76:79], v[218:221], v[88:91]
	s_setprio 0
	s_setprio 1
	v_mfma_f32_16x16x32_bf16 v[132:135], v[170:173], v[186:189], v[132:135]
	v_mfma_f32_16x16x32_bf16 v[128:131], v[178:181], v[186:189], v[128:131]
	v_mfma_f32_16x16x32_bf16 v[116:119], v[170:173], v[194:197], v[116:119]
	v_mfma_f32_16x16x32_bf16 v[112:115], v[178:181], v[194:197], v[112:115]
	v_mfma_f32_16x16x32_bf16 v[100:103], v[170:173], v[202:205], v[100:103]
	v_mfma_f32_16x16x32_bf16 v[96:99], v[178:181], v[202:205], v[96:99]
	v_mfma_f32_16x16x32_bf16 v[84:87], v[170:173], v[214:217], v[84:87]
	v_mfma_f32_16x16x32_bf16 v[80:83], v[178:181], v[214:217], v[80:83]
	v_mfma_f32_16x16x32_bf16 v[132:135], v[174:177], v[190:193], v[132:135]
	v_mfma_f32_16x16x32_bf16 v[128:131], v[182:185], v[190:193], v[128:131]
	v_mfma_f32_16x16x32_bf16 v[116:119], v[174:177], v[198:201], v[116:119]
	v_mfma_f32_16x16x32_bf16 v[112:115], v[182:185], v[198:201], v[112:115]
	v_mfma_f32_16x16x32_bf16 v[100:103], v[174:177], v[206:209], v[100:103]
	v_mfma_f32_16x16x32_bf16 v[96:99], v[182:185], v[206:209], v[96:99]
	v_mfma_f32_16x16x32_bf16 v[84:87], v[174:177], v[218:221], v[84:87]
	s_barrier
; #define PG8_STAGE(bufoff, gbase, voff) do { _Pragma("unroll") for (int _i = 0; _i < 2; ++_i) \
;         __builtin_amdgcn_global_load_lds((const unsigned*)((const char*)(gbase) + (voff)[_i]), (PG8_LAS unsigned*)(lds + (bufoff) + ldsw + _i * 8192), 16, 0, 0); } while (0)
; #define PG8_LDA(dst, b, h) do { _Pragma("unroll") for (int m = 0; m < 4; ++m) _Pragma("unroll") for (int k = 0; k < 2; ++k) dst[m][k] = *(const PG8_LAS bf16x8*)(lds + PG8_SA(b, h) + aoff + m * 2048 + k * 1024); } while (0)
; #define PG8_LDB(dst, b, h) do { _Pragma("unroll") for (int n = 0; n < 2; ++n) _Pragma("unroll") for (int k = 0; k < 2; ++k) dst[n][k] = *(const PG8_LAS bf16x8*)(lds + PG8_SB(b, h) + boff + n * 2048 + k * 1024); } while (0)
; #define PG8_MMA(ai, bj, At, Bt) do { __builtin_amdgcn_s_setprio(1); _Pragma("unroll") for (int m = 0; m < 4; ++m) _Pragma("unroll") for (int n = 0; n < 2; ++n) _Pragma("unroll") for (int k = 0; k < 2; ++k) \
;         acc[ai][bj][m][n] = __builtin_amdgcn_mfma_f32_16x16x32_bf16(Bt[n][k], At[m][k], acc[ai][bj][m][n], 0, 0, 0); __builtin_amdgcn_s_setprio(0); } while (0)
; #define PG8_WAIT_V(n) asm volatile("s_waitcnt vmcnt(" #n ")" ::: "memory")
; #define PG8_WAIT_L(n) asm volatile("s_waitcnt lgkmcnt(" #n ")" ::: "memory")
; #define PG8_BAR __builtin_amdgcn_s_barrier()
; #define PG8_SCHED __builtin_amdgcn_sched_barrier(0)
; template <class Epi, class Sched, bool ALIGN_EPI = false, bool SP2 = false>
; __device__ __forceinline__ void gemm_phase(PG8_LAS unsigned char* lds, const Gemm g, const Sched& S, const Epi& E) {
;     ...
;             PG8_LDB(B0, 1, 0); PG8_LDB(B1, 1, 1); PG8_SCHED; PG8_LDA(At, 1, 0); PG8_STAGE(PG8_SA(0, 1), a2 + hstepA, voffA);
;             PG8_WAIT_V(8); PG8_WAIT_L(0); PG8_BAR; PG8_MMA(0, 0, At, B0); PG8_MMA(0, 1, At, B1); PG8_BAR; PG8_SCHED;
;             PG8_LDA(At, 1, 1); PG8_STAGE(PG8_SB(1, 0), b3, voffB); PG8_STAGE(PG8_SB(1, 1), b3 + hstep, voffB); PG8_STAGE(PG8_SA(1, 0), a3, voffA);
;             PG8_WAIT_V(8); PG8_WAIT_L(0); PG8_BAR; PG8_MMA(1, 0, At, B0); PG8_MMA(1, 1, At, B1); PG8_BAR; PG8_SCHED;
	v_mfma_f32_16x16x32_bf16 v[80:83], v[182:185], v[218:221], v[80:83]
	s_setprio 0
	s_add_i32 s14, s35, s0
	v_lshl_add_u64 v[154:155], v[154:155], 0, s[22:23]
	s_mov_b32 m0, s14
	ds_read_b128 v[186:189], v168 offset:49152
	ds_read_b128 v[190:193], v168 offset:50176
	ds_read_b128 v[194:197], v168 offset:51200
	ds_read_b128 v[198:201], v168 offset:52224
	ds_read_b128 v[202:205], v168 offset:53248
	ds_read_b128 v[206:209], v168 offset:54272
	ds_read_b128 v[214:217], v168 offset:55296
	ds_read_b128 v[218:221], v168 offset:56320
	global_load_lds_dwordx4 v[154:155], off
	s_add_i32 m0, s14, 0x2000
	s_add_u32 s14, s40, 0x40080
	v_lshl_add_u64 v[154:155], v[210:211], 0, s[22:23]
	s_addc_u32 s15, s41, 0
	s_add_i32 s35, s36, s0
	global_load_lds_dwordx4 v[154:155], off
	v_lshl_add_u64 v[154:155], s[14:15], 0, v[212:213]
	s_mov_b32 m0, s35
	s_nop 0
	global_load_lds_dwordx4 v[154:155], off
	v_lshl_add_u64 v[154:155], s[14:15], 0, v[148:149]
	s_add_i32 m0, s35, 0x2000
	s_nop 0
	global_load_lds_dwordx4 v[154:155], off
	v_lshl_add_u64 v[154:155], v[222:223], 0, s[22:23]
	s_mov_b32 m0, s20
	s_nop 0
	global_load_lds_dwordx4 v[154:155], off
	v_lshl_add_u64 v[154:155], v[224:225], 0, s[22:23]
	s_mov_b32 m0, s21
	s_nop 0
	global_load_lds_dwordx4 v[154:155], off
	s_waitcnt vmcnt(8)
	s_waitcnt lgkmcnt(0)
	s_barrier
	s_setprio 1
	s_waitcnt lgkmcnt(0)
	v_mfma_f32_16x16x32_bf16 v[64:67], v[60:63], v[186:189], v[64:67]
	v_mfma_f32_16x16x32_bf16 v[56:59], v[72:75], v[186:189], v[56:59]
	v_mfma_f32_16x16x32_bf16 v[44:47], v[60:63], v[194:197], v[44:47]
	v_mfma_f32_16x16x32_bf16 v[40:43], v[72:75], v[194:197], v[40:43]
	v_mfma_f32_16x16x32_bf16 v[28:31], v[60:63], v[202:205], v[28:31]
	v_mfma_f32_16x16x32_bf16 v[24:27], v[72:75], v[202:205], v[24:27]
	v_mfma_f32_16x16x32_bf16 v[12:15], v[60:63], v[214:217], v[12:15]
	v_mfma_f32_16x16x32_bf16 v[8:11], v[72:75], v[214:217], v[8:11]
	v_mfma_f32_16x16x32_bf16 v[64:67], v[68:71], v[190:193], v[64:67]
	v_mfma_f32_16x16x32_bf16 v[56:59], v[76:79], v[190:193], v[56:59]
	v_mfma_f32_16x16x32_bf16 v[44:47], v[68:71], v[198:201], v[44:47]
	v_mfma_f32_16x16x32_bf16 v[40:43], v[76:79], v[198:201], v[40:43]
	v_mfma_f32_16x16x32_bf16 v[28:31], v[68:71], v[206:209], v[28:31]
	v_mfma_f32_16x16x32_bf16 v[24:27], v[76:79], v[206:209], v[24:27]
	v_mfma_f32_16x16x32_bf16 v[12:15], v[68:71], v[218:221], v[12:15]
	v_mfma_f32_16x16x32_bf16 v[8:11], v[76:79], v[218:221], v[8:11]
	s_setprio 0
	s_setprio 1
	v_mfma_f32_16x16x32_bf16 v[52:55], v[170:173], v[186:189], v[52:55]
	v_mfma_f32_16x16x32_bf16 v[48:51], v[178:181], v[186:189], v[48:51]
	v_mfma_f32_16x16x32_bf16 v[36:39], v[170:173], v[194:197], v[36:39]
	v_mfma_f32_16x16x32_bf16 v[32:35], v[178:181], v[194:197], v[32:35]
	v_mfma_f32_16x16x32_bf16 v[20:23], v[170:173], v[202:205], v[20:23]
	v_mfma_f32_16x16x32_bf16 v[16:19], v[178:181], v[202:205], v[16:19]
	v_mfma_f32_16x16x32_bf16 v[4:7], v[170:173], v[214:217], v[4:7]
	v_mfma_f32_16x16x32_bf16 v[0:3], v[178:181], v[214:217], v[0:3]
	v_mfma_f32_16x16x32_bf16 v[52:55], v[174:177], v[190:193], v[52:55]
	v_mfma_f32_16x16x32_bf16 v[48:51], v[182:185], v[190:193], v[48:51]
	v_mfma_f32_16x16x32_bf16 v[36:39], v[174:177], v[198:201], v[36:39]
	v_mfma_f32_16x16x32_bf16 v[32:35], v[182:185], v[198:201], v[32:35]
	v_mfma_f32_16x16x32_bf16 v[20:23], v[174:177], v[206:209], v[20:23]
	v_mfma_f32_16x16x32_bf16 v[16:19], v[182:185], v[206:209], v[16:19]
	v_mfma_f32_16x16x32_bf16 v[4:7], v[174:177], v[218:221], v[4:7]
	s_barrier
	v_mfma_f32_16x16x32_bf16 v[0:3], v[182:185], v[218:221], v[0:3]
	s_setprio 0
	s_nop 7
	s_add_i32 s34, s34, 2
	s_add_u32 s74, s74, 0x100
	s_addc_u32 s75, s75, 0
	s_add_u32 s30, s30, 0x100
	s_addc_u32 s31, s31, 0
	s_cmp_gt_u32 s34, 13
	s_cbranch_scc0 .LBB0_119
	s_and_b64 vcc, exec, s[62:63]
	s_cbranch_vccz .LBB0_122
	s_barrier

; #define PG8_STAGE(bufoff, gbase, voff) do { _Pragma("unroll") for (int _i = 0; _i < 2; ++_i) \
;         __builtin_amdgcn_global_load_lds((const unsigned*)((const char*)(gbase) + (voff)[_i]), (PG8_LAS unsigned*)(lds + (bufoff) + ldsw + _i * 8192), 16, 0, 0); } while (0)
; #define PG8_LDA(dst, b, h) do { _Pragma("unroll") for (int m = 0; m < 4; ++m) _Pragma("unroll") for (int k = 0; k < 2; ++k) dst[m][k] = *(const PG8_LAS bf16x8*)(lds + PG8_SA(b, h) + aoff + m * 2048 + k * 1024); } while (0)
; #define PG8_LDB(dst, b, h) do { _Pragma("unroll") for (int n = 0; n < 2; ++n) _Pragma("unroll") for (int k = 0; k < 2; ++k) dst[n][k] = *(const PG8_LAS bf16x8*)(lds + PG8_SB(b, h) + boff + n * 2048 + k * 1024); } while (0)
; #define PG8_WAIT_V(n) asm volatile("s_waitcnt vmcnt(" #n ")" ::: "memory")
; #define PG8_WAIT_L(n) asm volatile("s_waitcnt lgkmcnt(" #n ")" ::: "memory")
; #define PG8_BAR __builtin_amdgcn_s_barrier()
; #define PG8_SCHED __builtin_amdgcn_sched_barrier(0)
; template <class Epi, class Sched, bool ALIGN_EPI = false, bool SP2 = false>
; __device__ __forceinline__ void gemm_phase(PG8_LAS unsigned char* lds, const Gemm g, const Sched& S, const Epi& E) {
;     ...
;         for (int t = 0; t < nt; t += 2) {
;             const bool last = (t == nt - 2);
;             const char* a1 = cA + (g.gstrA ? (size_t)(t >> 2) * g.gstrA + (size_t)(t & 3) * kstep : (size_t)t * kstep) + kstep;
;             const char* a2 = last ? nA : cA + (g.gstrA ? (size_t)((t + 2) >> 2) * g.gstrA + (size_t)((t + 2) & 3) * kstep : (size_t)(t + 2) * kstep); const char* b2 = last ? nB : cB + (size_t)(t + 2) * kstep;
;             const char* a3 = a2 + kstep; const char* b3 = b2 + kstep;
;             if (last && has_next) S.a_ready(nxt);
;             if constexpr (Epi::HAS_PREFETCH) { if (t == nt - 4) E.prefetch(cur, tid, wid); }
;             if constexpr (SP2) {
;             PG8_LDB(B0, 0, 0); PG8_LDB(B1, 0, 1); PG8_SCHED; PG8_LDA(At, 0, 0); PG8_STAGE(PG8_SA(1, 1), a1 + hstepA, voffA);
;             PG8_WAIT_V(8); PG8_WAIT_L(0); PG8_BAR; PG8_MMA(0, 0, At, B0); PG8_MMA(0, 1, At, B1); PG8_BAR; PG8_SCHED;
;             PG8_LDA(At, 0, 1); PG8_STAGE(PG8_SB(0, 0), b2, voffB); PG8_STAGE(PG8_SB(0, 1), b2 + hstep, voffB); PG8_STAGE(PG8_SA(0, 0), a2, voffA);
;             PG8_WAIT_V(8); PG8_WAIT_L(0); PG8_BAR; PG8_MMA(1, 0, At, B0); PG8_MMA(1, 1, At, B1); PG8_BAR; PG8_SCHED;
.LBB0_183:
	s_add_u32 vcc_lo, s30, s40
	s_addc_u32 vcc_hi, s34, s41
	s_add_i32 s38, 0, 0x10000
	s_and_b64 s[12:13], exec, s[14:15]
	s_cselect_b32 s13, s91, vcc_hi
	s_cselect_b32 s12, s90, vcc_lo
	s_add_i32 vcc_lo, 0, 0x14000
	v_add_u32_e32 v140, s38, v240
	v_add_u32_e32 v156, vcc_lo, v240
	ds_read_b128 v[128:131], v140
	ds_read_b128 v[132:135], v140 offset:1024
	ds_read_b128 v[136:139], v140 offset:2048
	ds_read_b128 v[140:143], v140 offset:3072
	ds_read_b128 v[144:147], v156
	ds_read_b128 v[148:151], v156 offset:1024
	ds_read_b128 v[152:155], v156 offset:2048
	ds_read_b128 v[156:159], v156 offset:3072
	s_add_u32 s14, s24, s94
	s_addc_u32 s15, s26, s95
	v_lshl_add_u64 v[198:199], s[14:15], 0, v[192:193]
	v_lshl_add_u64 v[198:199], v[198:199], 0, s[22:23]
	s_add_i32 m0, s52, 0xc000
	ds_read_b128 v[160:163], v243
	ds_read_b128 v[164:167], v243 offset:1024
	ds_read_b128 v[168:171], v243 offset:2048
	ds_read_b128 v[172:175], v243 offset:3072
	ds_read_b128 v[176:179], v243 offset:4096
	ds_read_b128 v[180:183], v243 offset:5120
	ds_read_b128 v[184:187], v243 offset:6144
	ds_read_b128 v[188:191], v243 offset:7168
	global_load_lds_dwordx4 v[198:199], off
	v_lshl_add_u64 v[198:199], s[14:15], 0, v[194:195]
	v_lshl_add_u64 v[198:199], v[198:199], 0, s[22:23]
	s_add_i32 m0, s52, 0xe000
	s_nop 0
	global_load_lds_dwordx4 v[198:199], off
	s_waitcnt vmcnt(8)
	s_waitcnt lgkmcnt(0)
	s_barrier
	s_setprio 1
	s_waitcnt lgkmcnt(0)
	v_mfma_f32_16x16x32_bf16 v[124:127], v[128:131], v[160:163], v[124:127]
	v_mfma_f32_16x16x32_bf16 v[120:123], v[136:139], v[160:163], v[120:123]
	v_mfma_f32_16x16x32_bf16 v[108:111], v[128:131], v[168:171], v[108:111]
	v_mfma_f32_16x16x32_bf16 v[104:107], v[136:139], v[168:171], v[104:107]
	v_mfma_f32_16x16x32_bf16 v[92:95], v[128:131], v[176:179], v[92:95]
	v_mfma_f32_16x16x32_bf16 v[88:91], v[136:139], v[176:179], v[88:91]
	v_mfma_f32_16x16x32_bf16 v[76:79], v[128:131], v[184:187], v[76:79]
	v_mfma_f32_16x16x32_bf16 v[72:75], v[136:139], v[184:187], v[72:75]
	v_mfma_f32_16x16x32_bf16 v[124:127], v[132:135], v[164:167], v[124:127]
	v_mfma_f32_16x16x32_bf16 v[120:123], v[140:143], v[164:167], v[120:123]
	v_mfma_f32_16x16x32_bf16 v[108:111], v[132:135], v[172:175], v[108:111]
	v_mfma_f32_16x16x32_bf16 v[104:107], v[140:143], v[172:175], v[104:107]
	v_mfma_f32_16x16x32_bf16 v[92:95], v[132:135], v[180:183], v[92:95]
	v_mfma_f32_16x16x32_bf16 v[88:91], v[140:143], v[180:183], v[88:91]
	v_mfma_f32_16x16x32_bf16 v[76:79], v[132:135], v[188:191], v[76:79]
	v_mfma_f32_16x16x32_bf16 v[72:75], v[140:143], v[188:191], v[72:75]
	s_setprio 0
	s_setprio 1
	v_mfma_f32_16x16x32_bf16 v[116:119], v[144:147], v[160:163], v[116:119]
	v_mfma_f32_16x16x32_bf16 v[112:115], v[152:155], v[160:163], v[112:115]
	v_mfma_f32_16x16x32_bf16 v[100:103], v[144:147], v[168:171], v[100:103]
	v_mfma_f32_16x16x32_bf16 v[96:99], v[152:155], v[168:171], v[96:99]
	v_mfma_f32_16x16x32_bf16 v[84:87], v[144:147], v[176:179], v[84:87]
	v_mfma_f32_16x16x32_bf16 v[80:83], v[152:155], v[176:179], v[80:83]
	v_mfma_f32_16x16x32_bf16 v[68:71], v[144:147], v[184:187], v[68:71]
	v_mfma_f32_16x16x32_bf16 v[64:67], v[152:155], v[184:187], v[64:67]
	v_mfma_f32_16x16x32_bf16 v[116:119], v[148:151], v[164:167], v[116:119]
	v_mfma_f32_16x16x32_bf16 v[112:115], v[156:159], v[164:167], v[112:115]
	v_mfma_f32_16x16x32_bf16 v[100:103], v[148:151], v[172:175], v[100:103]
	v_mfma_f32_16x16x32_bf16 v[96:99], v[156:159], v[172:175], v[96:99]
	v_mfma_f32_16x16x32_bf16 v[84:87], v[148:151], v[180:183], v[84:87]
	v_mfma_f32_16x16x32_bf16 v[80:83], v[156:159], v[180:183], v[80:83]
	v_mfma_f32_16x16x32_bf16 v[68:71], v[148:151], v[188:191], v[68:71]
	s_barrier
	v_mfma_f32_16x16x32_bf16 v[64:67], v[156:159], v[188:191], v[64:67]
	s_setprio 0
	s_add_i32 s14, s38, s55
	v_lshl_add_u64 v[198:199], s[12:13], 0, v[212:213]
	s_mov_b32 m0, s14
	ds_read_b128 v[160:163], v243 offset:16384
	ds_read_b128 v[164:167], v243 offset:17408
	ds_read_b128 v[168:171], v243 offset:18432
	ds_read_b128 v[172:175], v243 offset:19456
	ds_read_b128 v[176:179], v243 offset:20480
	ds_read_b128 v[180:183], v243 offset:21504
	ds_read_b128 v[184:187], v243 offset:22528
	ds_read_b128 v[188:191], v243 offset:23552
	global_load_lds_dwordx4 v[198:199], off
	s_add_i32 m0, s14, 0x2000
	v_lshl_add_u64 v[200:201], s[12:13], 0, v[196:197]
	s_add_u32 s12, s12, s25
	s_addc_u32 s13, s13, 0
	s_add_i32 s14, vcc_lo, s55
	global_load_lds_dwordx4 v[200:201], off
	v_lshl_add_u64 v[202:203], s[12:13], 0, v[212:213]
	s_mov_b32 m0, s14
	v_lshl_add_u64 v[204:205], s[12:13], 0, v[196:197]
	global_load_lds_dwordx4 v[202:203], off
	s_add_i32 m0, s14, 0x2000
	v_lshl_add_u64 v[206:207], s[96:97], 0, v[192:193]
	global_load_lds_dwordx4 v[204:205], off
	s_mov_b32 m0, s52
	v_lshl_add_u64 v[208:209], s[96:97], 0, v[194:195]
	global_load_lds_dwordx4 v[206:207], off
	s_mov_b32 m0, s31
	s_nop 0
	global_load_lds_dwordx4 v[208:209], off
	s_waitcnt vmcnt(8)
	s_waitcnt lgkmcnt(0)
	s_barrier
; #define PG8_STAGE(bufoff, gbase, voff) do { _Pragma("unroll") for (int _i = 0; _i < 2; ++_i) \
;         __builtin_amdgcn_global_load_lds((const unsigned*)((const char*)(gbase) + (voff)[_i]), (PG8_LAS unsigned*)(lds + (bufoff) + ldsw + _i * 8192), 16, 0, 0); } while (0)
; #define PG8_LDA(dst, b, h) do { _Pragma("unroll") for (int m = 0; m < 4; ++m) _Pragma("unroll") for (int k = 0; k < 2; ++k) dst[m][k] = *(const PG8_LAS bf16x8*)(lds + PG8_SA(b, h) + aoff + m * 2048 + k * 1024); } while (0)
; #define PG8_LDB(dst, b, h) do { _Pragma("unroll") for (int n = 0; n < 2; ++n) _Pragma("unroll") for (int k = 0; k < 2; ++k) dst[n][k] = *(const PG8_LAS bf16x8*)(lds + PG8_SB(b, h) + boff + n * 2048 + k * 1024); } while (0)
; #define PG8_MMA(ai, bj, At, Bt) do { __builtin_amdgcn_s_setprio(1); _Pragma("unroll") for (int m = 0; m < 4; ++m) _Pragma("unroll") for (int n = 0; n < 2; ++n) _Pragma("unroll") for (int k = 0; k < 2; ++k) \
;         acc[ai][bj][m][n] = __builtin_amdgcn_mfma_f32_16x16x32_bf16(Bt[n][k], At[m][k], acc[ai][bj][m][n], 0, 0, 0); __builtin_amdgcn_s_setprio(0); } while (0)
; #define PG8_WAIT_V(n) asm volatile("s_waitcnt vmcnt(" #n ")" ::: "memory")
; #define PG8_WAIT_L(n) asm volatile("s_waitcnt lgkmcnt(" #n ")" ::: "memory")
; #define PG8_BAR __builtin_amdgcn_s_barrier()
; #define PG8_SCHED __builtin_amdgcn_sched_barrier(0)
; template <class Epi, class Sched, bool ALIGN_EPI = false, bool SP2 = false>
; __device__ __forceinline__ void gemm_phase(PG8_LAS unsigned char* lds, const Gemm g, const Sched& S, const Epi& E) {
;     ...
;             PG8_LDA(At, 0, 1); PG8_STAGE(PG8_SB(0, 0), b2, voffB); PG8_STAGE(PG8_SB(0, 1), b2 + hstep, voffB); PG8_STAGE(PG8_SA(0, 0), a2, voffA);
;             PG8_WAIT_V(8); PG8_WAIT_L(0); PG8_BAR; PG8_MMA(1, 0, At, B0); PG8_MMA(1, 1, At, B1); PG8_BAR; PG8_SCHED;
;             PG8_LDB(B0, 1, 0); PG8_LDB(B1, 1, 1); PG8_SCHED; PG8_LDA(At, 1, 0); PG8_STAGE(PG8_SA(0, 1), a2 + hstepA, voffA);
;             PG8_WAIT_V(8); PG8_WAIT_L(0); PG8_BAR; PG8_MMA(0, 0, At, B0); PG8_MMA(0, 1, At, B1); PG8_BAR; PG8_SCHED;
	s_setprio 1
	s_waitcnt lgkmcnt(0)
	v_mfma_f32_16x16x32_bf16 v[60:63], v[128:131], v[160:163], v[60:63]
	v_mfma_f32_16x16x32_bf16 v[56:59], v[136:139], v[160:163], v[56:59]
	v_mfma_f32_16x16x32_bf16 v[44:47], v[128:131], v[168:171], v[44:47]
	v_mfma_f32_16x16x32_bf16 v[40:43], v[136:139], v[168:171], v[40:43]
	v_mfma_f32_16x16x32_bf16 v[28:31], v[128:131], v[176:179], v[28:31]
	v_mfma_f32_16x16x32_bf16 v[24:27], v[136:139], v[176:179], v[24:27]
	v_mfma_f32_16x16x32_bf16 v[12:15], v[128:131], v[184:187], v[12:15]
	v_mfma_f32_16x16x32_bf16 v[8:11], v[136:139], v[184:187], v[8:11]
	v_mfma_f32_16x16x32_bf16 v[60:63], v[132:135], v[164:167], v[60:63]
	v_mfma_f32_16x16x32_bf16 v[56:59], v[140:143], v[164:167], v[56:59]
	v_mfma_f32_16x16x32_bf16 v[44:47], v[132:135], v[172:175], v[44:47]
	v_mfma_f32_16x16x32_bf16 v[40:43], v[140:143], v[172:175], v[40:43]
	v_mfma_f32_16x16x32_bf16 v[28:31], v[132:135], v[180:183], v[28:31]
	v_mfma_f32_16x16x32_bf16 v[24:27], v[140:143], v[180:183], v[24:27]
	v_mfma_f32_16x16x32_bf16 v[12:15], v[132:135], v[188:191], v[12:15]
	v_mfma_f32_16x16x32_bf16 v[8:11], v[140:143], v[188:191], v[8:11]
	s_setprio 0
	s_setprio 1
	v_mfma_f32_16x16x32_bf16 v[52:55], v[144:147], v[160:163], v[52:55]
	v_mfma_f32_16x16x32_bf16 v[48:51], v[152:155], v[160:163], v[48:51]
	v_mfma_f32_16x16x32_bf16 v[36:39], v[144:147], v[168:171], v[36:39]
	v_mfma_f32_16x16x32_bf16 v[32:35], v[152:155], v[168:171], v[32:35]
	v_mfma_f32_16x16x32_bf16 v[20:23], v[144:147], v[176:179], v[20:23]
	v_mfma_f32_16x16x32_bf16 v[16:19], v[152:155], v[176:179], v[16:19]
	v_mfma_f32_16x16x32_bf16 v[4:7], v[144:147], v[184:187], v[4:7]
	v_mfma_f32_16x16x32_bf16 v[0:3], v[152:155], v[184:187], v[0:3]
	v_mfma_f32_16x16x32_bf16 v[52:55], v[148:151], v[164:167], v[52:55]
	v_mfma_f32_16x16x32_bf16 v[48:51], v[156:159], v[164:167], v[48:51]
	v_mfma_f32_16x16x32_bf16 v[36:39], v[148:151], v[172:175], v[36:39]
	v_mfma_f32_16x16x32_bf16 v[32:35], v[156:159], v[172:175], v[32:35]
	v_mfma_f32_16x16x32_bf16 v[20:23], v[148:151], v[180:183], v[20:23]
	v_mfma_f32_16x16x32_bf16 v[16:19], v[156:159], v[180:183], v[16:19]
	v_mfma_f32_16x16x32_bf16 v[4:7], v[148:151], v[188:191], v[4:7]
	s_barrier
	v_mfma_f32_16x16x32_bf16 v[0:3], v[156:159], v[188:191], v[0:3]
	s_setprio 0
	s_add_i32 s14, 0, 0x18000
	s_add_i32 s15, 0, 0x1c000
	v_add_u32_e32 v140, s14, v240
	v_add_u32_e32 v156, s15, v240
	ds_read_b128 v[128:131], v140
	ds_read_b128 v[132:135], v140 offset:1024
	ds_read_b128 v[136:139], v140 offset:2048
	ds_read_b128 v[140:143], v140 offset:3072
	ds_read_b128 v[144:147], v156
	ds_read_b128 v[148:151], v156 offset:1024
	ds_read_b128 v[152:155], v156 offset:2048
	ds_read_b128 v[156:159], v156 offset:3072
	s_add_u32 s12, s96, s21
	s_addc_u32 s13, s97, s20
	s_mov_b32 m0, s35
	v_lshl_add_u64 v[210:211], s[12:13], 0, v[192:193]
	ds_read_b128 v[160:163], v243 offset:32768
	ds_read_b128 v[164:167], v243 offset:33792
	ds_read_b128 v[168:171], v243 offset:34816
	ds_read_b128 v[172:175], v243 offset:35840
	ds_read_b128 v[176:179], v243 offset:36864
	ds_read_b128 v[180:183], v243 offset:37888
	ds_read_b128 v[184:187], v243 offset:38912
	ds_read_b128 v[188:191], v243 offset:39936
	global_load_lds_dwordx4 v[210:211], off
	v_lshl_add_u64 v[210:211], s[12:13], 0, v[194:195]
	s_mov_b32 m0, s56
	s_nop 0
	global_load_lds_dwordx4 v[210:211], off
	s_waitcnt vmcnt(8)
	s_waitcnt lgkmcnt(0)
	s_barrier
	s_setprio 1
	s_waitcnt lgkmcnt(0)
	v_mfma_f32_16x16x32_bf16 v[124:127], v[128:131], v[160:163], v[124:127]
	v_mfma_f32_16x16x32_bf16 v[120:123], v[136:139], v[160:163], v[120:123]
	v_mfma_f32_16x16x32_bf16 v[108:111], v[128:131], v[168:171], v[108:111]
	v_mfma_f32_16x16x32_bf16 v[104:107], v[136:139], v[168:171], v[104:107]
	v_mfma_f32_16x16x32_bf16 v[92:95], v[128:131], v[176:179], v[92:95]
	v_mfma_f32_16x16x32_bf16 v[88:91], v[136:139], v[176:179], v[88:91]
	v_mfma_f32_16x16x32_bf16 v[76:79], v[128:131], v[184:187], v[76:79]
	v_mfma_f32_16x16x32_bf16 v[72:75], v[136:139], v[184:187], v[72:75]
	v_mfma_f32_16x16x32_bf16 v[124:127], v[132:135], v[164:167], v[124:127]
	v_mfma_f32_16x16x32_bf16 v[120:123], v[140:143], v[164:167], v[120:123]
	v_mfma_f32_16x16x32_bf16 v[108:111], v[132:135], v[172:175], v[108:111]
	v_mfma_f32_16x16x32_bf16 v[104:107], v[140:143], v[172:175], v[104:107]
	v_mfma_f32_16x16x32_bf16 v[92:95], v[132:135], v[180:183], v[92:95]
	v_mfma_f32_16x16x32_bf16 v[88:91], v[140:143], v[180:183], v[88:91]
	v_mfma_f32_16x16x32_bf16 v[76:79], v[132:135], v[188:191], v[76:79]
	v_mfma_f32_16x16x32_bf16 v[72:75], v[140:143], v[188:191], v[72:75]
	s_setprio 0
	s_setprio 1
	v_mfma_f32_16x16x32_bf16 v[116:119], v[144:147], v[160:163], v[116:119]
	v_mfma_f32_16x16x32_bf16 v[112:115], v[152:155], v[160:163], v[112:115]
	v_mfma_f32_16x16x32_bf16 v[100:103], v[144:147], v[168:171], v[100:103]
	v_mfma_f32_16x16x32_bf16 v[96:99], v[152:155], v[168:171], v[96:99]
	v_mfma_f32_16x16x32_bf16 v[84:87], v[144:147], v[176:179], v[84:87]
	v_mfma_f32_16x16x32_bf16 v[80:83], v[152:155], v[176:179], v[80:83]
	v_mfma_f32_16x16x32_bf16 v[68:71], v[144:147], v[184:187], v[68:71]
	v_mfma_f32_16x16x32_bf16 v[64:67], v[152:155], v[184:187], v[64:67]
	v_mfma_f32_16x16x32_bf16 v[116:119], v[148:151], v[164:167], v[116:119]
	v_mfma_f32_16x16x32_bf16 v[112:115], v[156:159], v[164:167], v[112:115]
	v_mfma_f32_16x16x32_bf16 v[100:103], v[148:151], v[172:175], v[100:103]
	v_mfma_f32_16x16x32_bf16 v[96:99], v[156:159], v[172:175], v[96:99]
	v_mfma_f32_16x16x32_bf16 v[84:87], v[148:151], v[180:183], v[84:87]
	v_mfma_f32_16x16x32_bf16 v[80:83], v[156:159], v[180:183], v[80:83]
	v_mfma_f32_16x16x32_bf16 v[68:71], v[148:151], v[188:191], v[68:71]
	s_barrier
; #define PG8_STAGE(bufoff, gbase, voff) do { _Pragma("unroll") for (int _i = 0; _i < 2; ++_i) \
;         __builtin_amdgcn_global_load_lds((const unsigned*)((const char*)(gbase) + (voff)[_i]), (PG8_LAS unsigned*)(lds + (bufoff) + ldsw + _i * 8192), 16, 0, 0); } while (0)
; #define PG8_LDA(dst, b, h) do { _Pragma("unroll") for (int m = 0; m < 4; ++m) _Pragma("unroll") for (int k = 0; k < 2; ++k) dst[m][k] = *(const PG8_LAS bf16x8*)(lds + PG8_SA(b, h) + aoff + m * 2048 + k * 1024); } while (0)
; #define PG8_LDB(dst, b, h) do { _Pragma("unroll") for (int n = 0; n < 2; ++n) _Pragma("unroll") for (int k = 0; k < 2; ++k) dst[n][k] = *(const PG8_LAS bf16x8*)(lds + PG8_SB(b, h) + boff + n * 2048 + k * 1024); } while (0)
; #define PG8_MMA(ai, bj, At, Bt) do { __builtin_amdgcn_s_setprio(1); _Pragma("unroll") for (int m = 0; m < 4; ++m) _Pragma("unroll") for (int n = 0; n < 2; ++n) _Pragma("unroll") for (int k = 0; k < 2; ++k) \
;         acc[ai][bj][m][n] = __builtin_amdgcn_mfma_f32_16x16x32_bf16(Bt[n][k], At[m][k], acc[ai][bj][m][n], 0, 0, 0); __builtin_amdgcn_s_setprio(0); } while (0)
; #define PG8_WAIT_V(n) asm volatile("s_waitcnt vmcnt(" #n ")" ::: "memory")
; #define PG8_WAIT_L(n) asm volatile("s_waitcnt lgkmcnt(" #n ")" ::: "memory")
; #define PG8_BAR __builtin_amdgcn_s_barrier()
; #define PG8_SCHED __builtin_amdgcn_sched_barrier(0)
; template <class Epi, class Sched, bool ALIGN_EPI = false, bool SP2 = false>
; __device__ __forceinline__ void gemm_phase(PG8_LAS unsigned char* lds, const Gemm g, const Sched& S, const Epi& E) {
;     ...
;             PG8_LDB(B0, 1, 0); PG8_LDB(B1, 1, 1); PG8_SCHED; PG8_LDA(At, 1, 0); PG8_STAGE(PG8_SA(0, 1), a2 + hstepA, voffA);
;             PG8_WAIT_V(8); PG8_WAIT_L(0); PG8_BAR; PG8_MMA(0, 0, At, B0); PG8_MMA(0, 1, At, B1); PG8_BAR; PG8_SCHED;
;             PG8_LDA(At, 1, 1); PG8_STAGE(PG8_SB(1, 0), b3, voffB); PG8_STAGE(PG8_SB(1, 1), b3 + hstep, voffB); PG8_STAGE(PG8_SA(1, 0), a3, voffA);
;             PG8_WAIT_V(8); PG8_WAIT_L(0); PG8_BAR; PG8_MMA(1, 0, At, B0); PG8_MMA(1, 1, At, B1); PG8_BAR; PG8_SCHED;
	v_mfma_f32_16x16x32_bf16 v[64:67], v[156:159], v[188:191], v[64:67]
	s_setprio 0
	s_add_i32 s12, s14, s55
	v_lshl_add_u64 v[198:199], v[198:199], 0, s[22:23]
	s_mov_b32 m0, s12
	ds_read_b128 v[160:163], v243 offset:49152
	ds_read_b128 v[164:167], v243 offset:50176
	ds_read_b128 v[168:171], v243 offset:51200
	ds_read_b128 v[172:175], v243 offset:52224
	ds_read_b128 v[176:179], v243 offset:53248
	ds_read_b128 v[180:183], v243 offset:54272
	ds_read_b128 v[184:187], v243 offset:55296
	ds_read_b128 v[188:191], v243 offset:56320
	global_load_lds_dwordx4 v[198:199], off
	v_lshl_add_u64 v[198:199], v[200:201], 0, s[22:23]
	s_add_i32 m0, s12, 0x2000
	s_add_i32 s12, s15, s55
	global_load_lds_dwordx4 v[198:199], off
	v_lshl_add_u64 v[198:199], v[202:203], 0, s[22:23]
	s_mov_b32 m0, s12
	s_nop 0
	global_load_lds_dwordx4 v[198:199], off
	v_lshl_add_u64 v[198:199], v[204:205], 0, s[22:23]
	s_add_i32 m0, s12, 0x2000
	s_nop 0
	global_load_lds_dwordx4 v[198:199], off
	v_lshl_add_u64 v[198:199], v[206:207], 0, s[22:23]
	s_mov_b32 m0, s17
	s_nop 0
	global_load_lds_dwordx4 v[198:199], off
	v_lshl_add_u64 v[198:199], v[208:209], 0, s[22:23]
	s_mov_b32 m0, s27
	s_nop 0
	global_load_lds_dwordx4 v[198:199], off
	s_waitcnt vmcnt(8)
	s_waitcnt lgkmcnt(0)
	s_barrier
	s_setprio 1
	s_waitcnt lgkmcnt(0)
	v_mfma_f32_16x16x32_bf16 v[60:63], v[128:131], v[160:163], v[60:63]
	v_mfma_f32_16x16x32_bf16 v[56:59], v[136:139], v[160:163], v[56:59]
	v_mfma_f32_16x16x32_bf16 v[44:47], v[128:131], v[168:171], v[44:47]
	v_mfma_f32_16x16x32_bf16 v[40:43], v[136:139], v[168:171], v[40:43]
	v_mfma_f32_16x16x32_bf16 v[28:31], v[128:131], v[176:179], v[28:31]
	v_mfma_f32_16x16x32_bf16 v[24:27], v[136:139], v[176:179], v[24:27]
	v_mfma_f32_16x16x32_bf16 v[12:15], v[128:131], v[184:187], v[12:15]
	v_mfma_f32_16x16x32_bf16 v[8:11], v[136:139], v[184:187], v[8:11]
	v_mfma_f32_16x16x32_bf16 v[60:63], v[132:135], v[164:167], v[60:63]
	v_mfma_f32_16x16x32_bf16 v[56:59], v[140:143], v[164:167], v[56:59]
	v_mfma_f32_16x16x32_bf16 v[44:47], v[132:135], v[172:175], v[44:47]
	v_mfma_f32_16x16x32_bf16 v[40:43], v[140:143], v[172:175], v[40:43]
	v_mfma_f32_16x16x32_bf16 v[28:31], v[132:135], v[180:183], v[28:31]
	v_mfma_f32_16x16x32_bf16 v[24:27], v[140:143], v[180:183], v[24:27]
	v_mfma_f32_16x16x32_bf16 v[12:15], v[132:135], v[188:191], v[12:15]
	v_mfma_f32_16x16x32_bf16 v[8:11], v[140:143], v[188:191], v[8:11]
	s_setprio 0
	s_setprio 1
	v_mfma_f32_16x16x32_bf16 v[52:55], v[144:147], v[160:163], v[52:55]
	v_mfma_f32_16x16x32_bf16 v[48:51], v[152:155], v[160:163], v[48:51]
	v_mfma_f32_16x16x32_bf16 v[36:39], v[144:147], v[168:171], v[36:39]
	v_mfma_f32_16x16x32_bf16 v[32:35], v[152:155], v[168:171], v[32:35]
	v_mfma_f32_16x16x32_bf16 v[20:23], v[144:147], v[176:179], v[20:23]
	v_mfma_f32_16x16x32_bf16 v[16:19], v[152:155], v[176:179], v[16:19]
	v_mfma_f32_16x16x32_bf16 v[4:7], v[144:147], v[184:187], v[4:7]
	v_mfma_f32_16x16x32_bf16 v[0:3], v[152:155], v[184:187], v[0:3]
	v_mfma_f32_16x16x32_bf16 v[52:55], v[148:151], v[164:167], v[52:55]
	v_mfma_f32_16x16x32_bf16 v[48:51], v[156:159], v[164:167], v[48:51]
	v_mfma_f32_16x16x32_bf16 v[36:39], v[148:151], v[172:175], v[36:39]
	v_mfma_f32_16x16x32_bf16 v[32:35], v[156:159], v[172:175], v[32:35]
	v_mfma_f32_16x16x32_bf16 v[20:23], v[148:151], v[180:183], v[20:23]
	v_mfma_f32_16x16x32_bf16 v[16:19], v[156:159], v[180:183], v[16:19]
	v_mfma_f32_16x16x32_bf16 v[4:7], v[148:151], v[188:191], v[4:7]
	s_barrier
	v_mfma_f32_16x16x32_bf16 v[0:3], v[156:159], v[188:191], v[0:3]
	s_setprio 0
	s_nop 7
	s_add_i32 s12, s36, 2
	s_add_u32 s40, s40, 0x100
	s_addc_u32 s41, s41, 0
	s_cmp_ge_u32 s36, s16
	s_mov_b32 s36, s12
	s_cbranch_scc1 .LBB0_191

; #define PG8_STAGE(bufoff, gbase, voff) do { _Pragma("unroll") for (int _i = 0; _i < 2; ++_i) \
;         __builtin_amdgcn_global_load_lds((const unsigned*)((const char*)(gbase) + (voff)[_i]), (PG8_LAS unsigned*)(lds + (bufoff) + ldsw + _i * 8192), 16, 0, 0); } while (0)
; #define PG8_LDA(dst, b, h) do { _Pragma("unroll") for (int m = 0; m < 4; ++m) _Pragma("unroll") for (int k = 0; k < 2; ++k) dst[m][k] = *(const PG8_LAS bf16x8*)(lds + PG8_SA(b, h) + aoff + m * 2048 + k * 1024); } while (0)
; #define PG8_LDB(dst, b, h) do { _Pragma("unroll") for (int n = 0; n < 2; ++n) _Pragma("unroll") for (int k = 0; k < 2; ++k) dst[n][k] = *(const PG8_LAS bf16x8*)(lds + PG8_SB(b, h) + boff + n * 2048 + k * 1024); } while (0)
; #define PG8_WAIT_V(n) asm volatile("s_waitcnt vmcnt(" #n ")" ::: "memory")
; #define PG8_WAIT_L(n) asm volatile("s_waitcnt lgkmcnt(" #n ")" ::: "memory")
; #define PG8_BAR __builtin_amdgcn_s_barrier()
; #define PG8_SCHED __builtin_amdgcn_sched_barrier(0)
; template <class Epi, class Sched, bool ALIGN_EPI = false, bool SP2 = false>
; __device__ __forceinline__ void gemm_phase(PG8_LAS unsigned char* lds, const Gemm g, const Sched& S, const Epi& E) {
;     ...
;         for (int t = 0; t < nt; t += 2) {
;             const bool last = (t == nt - 2);
;             const char* a1 = cA + (g.gstrA ? (size_t)(t >> 2) * g.gstrA + (size_t)(t & 3) * kstep : (size_t)t * kstep) + kstep;
;             const char* a2 = last ? nA : cA + (g.gstrA ? (size_t)((t + 2) >> 2) * g.gstrA + (size_t)((t + 2) & 3) * kstep : (size_t)(t + 2) * kstep); const char* b2 = last ? nB : cB + (size_t)(t + 2) * kstep;
;             const char* a3 = a2 + kstep; const char* b3 = b2 + kstep;
;             if (last && has_next) S.a_ready(nxt);
;             if constexpr (Epi::HAS_PREFETCH) { if (t == nt - 4) E.prefetch(cur, tid, wid); }
;             if constexpr (SP2) {
;             PG8_LDB(B0, 0, 0); PG8_LDB(B1, 0, 1); PG8_SCHED; PG8_LDA(At, 0, 0); PG8_STAGE(PG8_SA(1, 1), a1 + hstepA, voffA);
;             PG8_WAIT_V(8); PG8_WAIT_L(0); PG8_BAR; PG8_MMA(0, 0, At, B0); PG8_MMA(0, 1, At, B1); PG8_BAR; PG8_SCHED;
;             PG8_LDA(At, 0, 1); PG8_STAGE(PG8_SB(0, 0), b2, voffB); PG8_STAGE(PG8_SB(0, 1), b2 + hstep, voffB); PG8_STAGE(PG8_SA(0, 0), a2, voffA);
;             PG8_WAIT_V(8); PG8_WAIT_L(0); PG8_BAR; PG8_MMA(1, 0, At, B0); PG8_MMA(1, 1, At, B1); PG8_BAR; PG8_SCHED;
.LBB0_369:
	s_add_u32 s14, s68, 0xfffc0080
	s_addc_u32 s15, s69, -1
	s_add_i32 s59, 0, 0x10000
	s_cmp_eq_u32 s52, 12
	s_cselect_b32 s15, s24, s15
	s_cselect_b32 s14, s26, s14
	s_cselect_b32 s41, s30, s37
	s_cselect_b32 s40, s34, s36
	s_add_i32 s61, 0, 0x14000
	v_add_u32_e32 v162, s59, v139
	v_add_u32_e32 v178, s61, v139
	ds_read_b128 v[150:153], v162
	ds_read_b128 v[154:157], v162 offset:1024
	ds_read_b128 v[158:161], v162 offset:2048
	ds_read_b128 v[162:165], v162 offset:3072
	ds_read_b128 v[166:169], v178
	ds_read_b128 v[170:173], v178 offset:1024
	ds_read_b128 v[174:177], v178 offset:2048
	ds_read_b128 v[178:181], v178 offset:3072
	v_lshl_add_u64 v[210:211], s[68:69], 0, v[134:135]
	s_add_i32 m0, s17, 0xc000
	ds_read_b128 v[182:185], v149
	ds_read_b128 v[186:189], v149 offset:1024
	ds_read_b128 v[190:193], v149 offset:2048
	ds_read_b128 v[194:197], v149 offset:3072
	ds_read_b128 v[198:201], v149 offset:4096
	ds_read_b128 v[202:205], v149 offset:5120
	ds_read_b128 v[206:209], v149 offset:6144
	ds_read_b128 v[214:217], v149 offset:7168
	global_load_lds_dwordx4 v[210:211], off
	v_lshl_add_u64 v[210:211], s[68:69], 0, v[136:137]
	s_add_i32 m0, s17, 0xe000
	s_nop 0
	global_load_lds_dwordx4 v[210:211], off
	s_waitcnt vmcnt(8)
	s_waitcnt lgkmcnt(0)
	s_barrier
	s_setprio 1
	s_waitcnt lgkmcnt(0)
	v_mfma_f32_16x16x32_bf16 v[124:127], v[150:153], v[182:185], v[124:127]
	v_mfma_f32_16x16x32_bf16 v[116:119], v[158:161], v[182:185], v[116:119]
	v_mfma_f32_16x16x32_bf16 v[108:111], v[150:153], v[190:193], v[108:111]
	v_mfma_f32_16x16x32_bf16 v[100:103], v[158:161], v[190:193], v[100:103]
	v_mfma_f32_16x16x32_bf16 v[92:95], v[150:153], v[198:201], v[92:95]
	v_mfma_f32_16x16x32_bf16 v[84:87], v[158:161], v[198:201], v[84:87]
	v_mfma_f32_16x16x32_bf16 v[76:79], v[150:153], v[206:209], v[76:79]
	v_mfma_f32_16x16x32_bf16 v[68:71], v[158:161], v[206:209], v[68:71]
	v_mfma_f32_16x16x32_bf16 v[124:127], v[154:157], v[186:189], v[124:127]
	v_mfma_f32_16x16x32_bf16 v[116:119], v[162:165], v[186:189], v[116:119]
	v_mfma_f32_16x16x32_bf16 v[108:111], v[154:157], v[194:197], v[108:111]
	v_mfma_f32_16x16x32_bf16 v[100:103], v[162:165], v[194:197], v[100:103]
	v_mfma_f32_16x16x32_bf16 v[92:95], v[154:157], v[202:205], v[92:95]
	v_mfma_f32_16x16x32_bf16 v[84:87], v[162:165], v[202:205], v[84:87]
	v_mfma_f32_16x16x32_bf16 v[76:79], v[154:157], v[214:217], v[76:79]
	v_mfma_f32_16x16x32_bf16 v[68:71], v[162:165], v[214:217], v[68:71]
	s_setprio 0
	s_setprio 1
	v_mfma_f32_16x16x32_bf16 v[120:123], v[166:169], v[182:185], v[120:123]
	v_mfma_f32_16x16x32_bf16 v[112:115], v[174:177], v[182:185], v[112:115]
	v_mfma_f32_16x16x32_bf16 v[104:107], v[166:169], v[190:193], v[104:107]
	v_mfma_f32_16x16x32_bf16 v[96:99], v[174:177], v[190:193], v[96:99]
	v_mfma_f32_16x16x32_bf16 v[88:91], v[166:169], v[198:201], v[88:91]
	v_mfma_f32_16x16x32_bf16 v[80:83], v[174:177], v[198:201], v[80:83]
	v_mfma_f32_16x16x32_bf16 v[72:75], v[166:169], v[206:209], v[72:75]
	v_mfma_f32_16x16x32_bf16 v[64:67], v[174:177], v[206:209], v[64:67]
	v_mfma_f32_16x16x32_bf16 v[120:123], v[170:173], v[186:189], v[120:123]
	v_mfma_f32_16x16x32_bf16 v[112:115], v[178:181], v[186:189], v[112:115]
	v_mfma_f32_16x16x32_bf16 v[104:107], v[170:173], v[194:197], v[104:107]
	v_mfma_f32_16x16x32_bf16 v[96:99], v[178:181], v[194:197], v[96:99]
	v_mfma_f32_16x16x32_bf16 v[88:91], v[170:173], v[202:205], v[88:91]
	v_mfma_f32_16x16x32_bf16 v[80:83], v[178:181], v[202:205], v[80:83]
	v_mfma_f32_16x16x32_bf16 v[72:75], v[170:173], v[214:217], v[72:75]
	s_barrier
	v_mfma_f32_16x16x32_bf16 v[64:67], v[178:181], v[214:217], v[64:67]
	s_setprio 0
	s_add_i32 s59, s59, s2
	v_lshl_add_u64 v[210:211], s[40:41], 0, v[212:213]
	s_mov_b32 m0, s59
	ds_read_b128 v[182:185], v149 offset:16384
	ds_read_b128 v[186:189], v149 offset:17408
	ds_read_b128 v[190:193], v149 offset:18432
	ds_read_b128 v[194:197], v149 offset:19456
	ds_read_b128 v[198:201], v149 offset:20480
	ds_read_b128 v[202:205], v149 offset:21504
	ds_read_b128 v[206:209], v149 offset:22528
	ds_read_b128 v[214:217], v149 offset:23552
	global_load_lds_dwordx4 v[210:211], off
	s_add_i32 m0, s59, 0x2000
	s_add_u32 s70, s40, 0x40000
	v_lshl_add_u64 v[218:219], s[40:41], 0, v[128:129]
	s_addc_u32 s71, s41, 0
	s_add_i32 s59, s61, s2
	global_load_lds_dwordx4 v[218:219], off
	v_lshl_add_u64 v[220:221], s[70:71], 0, v[212:213]
	s_mov_b32 m0, s59
	v_lshl_add_u64 v[222:223], s[14:15], 0, v[130:131]
	global_load_lds_dwordx4 v[220:221], off
	v_lshl_add_u64 v[220:221], s[70:71], 0, v[128:129]
	s_add_i32 m0, s59, 0x2000
	s_nop 0
	global_load_lds_dwordx4 v[220:221], off
	v_lshl_add_u64 v[220:221], s[14:15], 0, v[132:133]
	s_mov_b32 m0, s17
	s_nop 0
	global_load_lds_dwordx4 v[220:221], off
	s_mov_b32 m0, s18
	s_nop 0
	global_load_lds_dwordx4 v[222:223], off
	s_waitcnt vmcnt(8)
	s_waitcnt lgkmcnt(0)
	s_barrier
; #define PG8_STAGE(bufoff, gbase, voff) do { _Pragma("unroll") for (int _i = 0; _i < 2; ++_i) \
;         __builtin_amdgcn_global_load_lds((const unsigned*)((const char*)(gbase) + (voff)[_i]), (PG8_LAS unsigned*)(lds + (bufoff) + ldsw + _i * 8192), 16, 0, 0); } while (0)
; #define PG8_LDA(dst, b, h) do { _Pragma("unroll") for (int m = 0; m < 4; ++m) _Pragma("unroll") for (int k = 0; k < 2; ++k) dst[m][k] = *(const PG8_LAS bf16x8*)(lds + PG8_SA(b, h) + aoff + m * 2048 + k * 1024); } while (0)
; #define PG8_LDB(dst, b, h) do { _Pragma("unroll") for (int n = 0; n < 2; ++n) _Pragma("unroll") for (int k = 0; k < 2; ++k) dst[n][k] = *(const PG8_LAS bf16x8*)(lds + PG8_SB(b, h) + boff + n * 2048 + k * 1024); } while (0)
; #define PG8_MMA(ai, bj, At, Bt) do { __builtin_amdgcn_s_setprio(1); _Pragma("unroll") for (int m = 0; m < 4; ++m) _Pragma("unroll") for (int n = 0; n < 2; ++n) _Pragma("unroll") for (int k = 0; k < 2; ++k) \
;         acc[ai][bj][m][n] = __builtin_amdgcn_mfma_f32_16x16x32_bf16(Bt[n][k], At[m][k], acc[ai][bj][m][n], 0, 0, 0); __builtin_amdgcn_s_setprio(0); } while (0)
; #define PG8_WAIT_V(n) asm volatile("s_waitcnt vmcnt(" #n ")" ::: "memory")
; #define PG8_WAIT_L(n) asm volatile("s_waitcnt lgkmcnt(" #n ")" ::: "memory")
; #define PG8_BAR __builtin_amdgcn_s_barrier()
; #define PG8_SCHED __builtin_amdgcn_sched_barrier(0)
; template <class Epi, class Sched, bool ALIGN_EPI = false, bool SP2 = false>
; __device__ __forceinline__ void gemm_phase(PG8_LAS unsigned char* lds, const Gemm g, const Sched& S, const Epi& E) {
;     ...
;             PG8_LDA(At, 0, 1); PG8_STAGE(PG8_SB(0, 0), b2, voffB); PG8_STAGE(PG8_SB(0, 1), b2 + hstep, voffB); PG8_STAGE(PG8_SA(0, 0), a2, voffA);
;             PG8_WAIT_V(8); PG8_WAIT_L(0); PG8_BAR; PG8_MMA(1, 0, At, B0); PG8_MMA(1, 1, At, B1); PG8_BAR; PG8_SCHED;
;             PG8_LDB(B0, 1, 0); PG8_LDB(B1, 1, 1); PG8_SCHED; PG8_LDA(At, 1, 0); PG8_STAGE(PG8_SA(0, 1), a2 + hstepA, voffA);
;             PG8_WAIT_V(8); PG8_WAIT_L(0); PG8_BAR; PG8_MMA(0, 0, At, B0); PG8_MMA(0, 1, At, B1); PG8_BAR; PG8_SCHED;
	s_setprio 1
	s_waitcnt lgkmcnt(0)
	v_mfma_f32_16x16x32_bf16 v[60:63], v[150:153], v[182:185], v[60:63]
	v_mfma_f32_16x16x32_bf16 v[52:55], v[158:161], v[182:185], v[52:55]
	v_mfma_f32_16x16x32_bf16 v[44:47], v[150:153], v[190:193], v[44:47]
	v_mfma_f32_16x16x32_bf16 v[36:39], v[158:161], v[190:193], v[36:39]
	v_mfma_f32_16x16x32_bf16 v[28:31], v[150:153], v[198:201], v[28:31]
	v_mfma_f32_16x16x32_bf16 v[20:23], v[158:161], v[198:201], v[20:23]
	v_mfma_f32_16x16x32_bf16 v[12:15], v[150:153], v[206:209], v[12:15]
	v_mfma_f32_16x16x32_bf16 v[4:7], v[158:161], v[206:209], v[4:7]
	v_mfma_f32_16x16x32_bf16 v[60:63], v[154:157], v[186:189], v[60:63]
	v_mfma_f32_16x16x32_bf16 v[52:55], v[162:165], v[186:189], v[52:55]
	v_mfma_f32_16x16x32_bf16 v[44:47], v[154:157], v[194:197], v[44:47]
	v_mfma_f32_16x16x32_bf16 v[36:39], v[162:165], v[194:197], v[36:39]
	v_mfma_f32_16x16x32_bf16 v[28:31], v[154:157], v[202:205], v[28:31]
	v_mfma_f32_16x16x32_bf16 v[20:23], v[162:165], v[202:205], v[20:23]
	v_mfma_f32_16x16x32_bf16 v[12:15], v[154:157], v[214:217], v[12:15]
	v_mfma_f32_16x16x32_bf16 v[4:7], v[162:165], v[214:217], v[4:7]
	s_setprio 0
	s_setprio 1
	v_mfma_f32_16x16x32_bf16 v[56:59], v[166:169], v[182:185], v[56:59]
	v_mfma_f32_16x16x32_bf16 v[48:51], v[174:177], v[182:185], v[48:51]
	v_mfma_f32_16x16x32_bf16 v[40:43], v[166:169], v[190:193], v[40:43]
	v_mfma_f32_16x16x32_bf16 v[32:35], v[174:177], v[190:193], v[32:35]
	v_mfma_f32_16x16x32_bf16 v[24:27], v[166:169], v[198:201], v[24:27]
	v_mfma_f32_16x16x32_bf16 v[16:19], v[174:177], v[198:201], v[16:19]
	v_mfma_f32_16x16x32_bf16 v[8:11], v[166:169], v[206:209], v[8:11]
	v_mfma_f32_16x16x32_bf16 v[0:3], v[174:177], v[206:209], v[0:3]
	v_mfma_f32_16x16x32_bf16 v[56:59], v[170:173], v[186:189], v[56:59]
	v_mfma_f32_16x16x32_bf16 v[48:51], v[178:181], v[186:189], v[48:51]
	v_mfma_f32_16x16x32_bf16 v[40:43], v[170:173], v[194:197], v[40:43]
	v_mfma_f32_16x16x32_bf16 v[32:35], v[178:181], v[194:197], v[32:35]
	v_mfma_f32_16x16x32_bf16 v[24:27], v[170:173], v[202:205], v[24:27]
	v_mfma_f32_16x16x32_bf16 v[16:19], v[178:181], v[202:205], v[16:19]
	v_mfma_f32_16x16x32_bf16 v[8:11], v[170:173], v[214:217], v[8:11]
	s_barrier
	v_mfma_f32_16x16x32_bf16 v[0:3], v[178:181], v[214:217], v[0:3]
	s_setprio 0
	s_add_i32 s59, 0, 0x18000
	s_add_i32 s61, 0, 0x1c000
	v_add_u32_e32 v162, s59, v139
	v_add_u32_e32 v178, s61, v139
	ds_read_b128 v[150:153], v162
	ds_read_b128 v[154:157], v162 offset:1024
	ds_read_b128 v[158:161], v162 offset:2048
	ds_read_b128 v[162:165], v162 offset:3072
	ds_read_b128 v[166:169], v178
	ds_read_b128 v[170:173], v178 offset:1024
	ds_read_b128 v[174:177], v178 offset:2048
	ds_read_b128 v[178:181], v178 offset:3072
	s_add_u32 s14, s14, 0x40000
	s_addc_u32 s15, s15, 0
	s_mov_b32 m0, s20
	v_lshl_add_u64 v[224:225], s[14:15], 0, v[132:133]
	ds_read_b128 v[182:185], v149 offset:32768
	ds_read_b128 v[186:189], v149 offset:33792
	ds_read_b128 v[190:193], v149 offset:34816
	ds_read_b128 v[194:197], v149 offset:35840
	ds_read_b128 v[198:201], v149 offset:36864
	ds_read_b128 v[202:205], v149 offset:37888
	ds_read_b128 v[206:209], v149 offset:38912
	ds_read_b128 v[214:217], v149 offset:39936
	global_load_lds_dwordx4 v[224:225], off
	v_lshl_add_u64 v[224:225], s[14:15], 0, v[130:131]
	s_mov_b32 m0, s21
	s_nop 0
	global_load_lds_dwordx4 v[224:225], off
	s_waitcnt vmcnt(8)
	s_waitcnt lgkmcnt(0)
	s_barrier
	s_setprio 1
	s_waitcnt lgkmcnt(0)
	v_mfma_f32_16x16x32_bf16 v[124:127], v[150:153], v[182:185], v[124:127]
	v_mfma_f32_16x16x32_bf16 v[116:119], v[158:161], v[182:185], v[116:119]
	v_mfma_f32_16x16x32_bf16 v[108:111], v[150:153], v[190:193], v[108:111]
	v_mfma_f32_16x16x32_bf16 v[100:103], v[158:161], v[190:193], v[100:103]
	v_mfma_f32_16x16x32_bf16 v[92:95], v[150:153], v[198:201], v[92:95]
	v_mfma_f32_16x16x32_bf16 v[84:87], v[158:161], v[198:201], v[84:87]
	v_mfma_f32_16x16x32_bf16 v[76:79], v[150:153], v[206:209], v[76:79]
	v_mfma_f32_16x16x32_bf16 v[68:71], v[158:161], v[206:209], v[68:71]
	v_mfma_f32_16x16x32_bf16 v[124:127], v[154:157], v[186:189], v[124:127]
	v_mfma_f32_16x16x32_bf16 v[116:119], v[162:165], v[186:189], v[116:119]
	v_mfma_f32_16x16x32_bf16 v[108:111], v[154:157], v[194:197], v[108:111]
	v_mfma_f32_16x16x32_bf16 v[100:103], v[162:165], v[194:197], v[100:103]
	v_mfma_f32_16x16x32_bf16 v[92:95], v[154:157], v[202:205], v[92:95]
	v_mfma_f32_16x16x32_bf16 v[84:87], v[162:165], v[202:205], v[84:87]
	v_mfma_f32_16x16x32_bf16 v[76:79], v[154:157], v[214:217], v[76:79]
	v_mfma_f32_16x16x32_bf16 v[68:71], v[162:165], v[214:217], v[68:71]
	s_setprio 0
	s_setprio 1
	v_mfma_f32_16x16x32_bf16 v[120:123], v[166:169], v[182:185], v[120:123]
	v_mfma_f32_16x16x32_bf16 v[112:115], v[174:177], v[182:185], v[112:115]
	v_mfma_f32_16x16x32_bf16 v[104:107], v[166:169], v[190:193], v[104:107]
	v_mfma_f32_16x16x32_bf16 v[96:99], v[174:177], v[190:193], v[96:99]
	v_mfma_f32_16x16x32_bf16 v[88:91], v[166:169], v[198:201], v[88:91]
	v_mfma_f32_16x16x32_bf16 v[80:83], v[174:177], v[198:201], v[80:83]
	v_mfma_f32_16x16x32_bf16 v[72:75], v[166:169], v[206:209], v[72:75]
	v_mfma_f32_16x16x32_bf16 v[64:67], v[174:177], v[206:209], v[64:67]
	v_mfma_f32_16x16x32_bf16 v[120:123], v[170:173], v[186:189], v[120:123]
	v_mfma_f32_16x16x32_bf16 v[112:115], v[178:181], v[186:189], v[112:115]
	v_mfma_f32_16x16x32_bf16 v[104:107], v[170:173], v[194:197], v[104:107]
	v_mfma_f32_16x16x32_bf16 v[96:99], v[178:181], v[194:197], v[96:99]
	v_mfma_f32_16x16x32_bf16 v[88:91], v[170:173], v[202:205], v[88:91]
	v_mfma_f32_16x16x32_bf16 v[80:83], v[178:181], v[202:205], v[80:83]
	v_mfma_f32_16x16x32_bf16 v[72:75], v[170:173], v[214:217], v[72:75]
	s_barrier
; #define PG8_STAGE(bufoff, gbase, voff) do { _Pragma("unroll") for (int _i = 0; _i < 2; ++_i) \
;         __builtin_amdgcn_global_load_lds((const unsigned*)((const char*)(gbase) + (voff)[_i]), (PG8_LAS unsigned*)(lds + (bufoff) + ldsw + _i * 8192), 16, 0, 0); } while (0)
; #define PG8_LDA(dst, b, h) do { _Pragma("unroll") for (int m = 0; m < 4; ++m) _Pragma("unroll") for (int k = 0; k < 2; ++k) dst[m][k] = *(const PG8_LAS bf16x8*)(lds + PG8_SA(b, h) + aoff + m * 2048 + k * 1024); } while (0)
; #define PG8_MMA(ai, bj, At, Bt) do { __builtin_amdgcn_s_setprio(1); _Pragma("unroll") for (int m = 0; m < 4; ++m) _Pragma("unroll") for (int n = 0; n < 2; ++n) _Pragma("unroll") for (int k = 0; k < 2; ++k) \
;         acc[ai][bj][m][n] = __builtin_amdgcn_mfma_f32_16x16x32_bf16(Bt[n][k], At[m][k], acc[ai][bj][m][n], 0, 0, 0); __builtin_amdgcn_s_setprio(0); } while (0)
; #define PG8_WAIT_V(n) asm volatile("s_waitcnt vmcnt(" #n ")" ::: "memory")
; #define PG8_WAIT_L(n) asm volatile("s_waitcnt lgkmcnt(" #n ")" ::: "memory")
; #define PG8_BAR __builtin_amdgcn_s_barrier()
; #define PG8_SCHED __builtin_amdgcn_sched_barrier(0)
; template <class Epi, class Sched, bool ALIGN_EPI = false, bool SP2 = false>
; __device__ __forceinline__ void gemm_phase(PG8_LAS unsigned char* lds, const Gemm g, const Sched& S, const Epi& E) {
;     ...
;         for (int t = 0; t < nt; t += 2) {
;     ...
;             PG8_WAIT_V(8); PG8_WAIT_L(0); PG8_BAR; PG8_MMA(0, 0, At, B0); PG8_MMA(0, 1, At, B1); PG8_BAR; PG8_SCHED;
;             PG8_LDA(At, 1, 1); PG8_STAGE(PG8_SB(1, 0), b3, voffB); PG8_STAGE(PG8_SB(1, 1), b3 + hstep, voffB); PG8_STAGE(PG8_SA(1, 0), a3, voffA);
;             PG8_WAIT_V(8); PG8_WAIT_L(0); PG8_BAR; PG8_MMA(1, 0, At, B0); PG8_MMA(1, 1, At, B1); PG8_BAR; PG8_SCHED;
;     ...
;         if constexpr (ALIGN_EPI) { if (wr == 0) PG8_BAR; }
	v_mfma_f32_16x16x32_bf16 v[64:67], v[178:181], v[214:217], v[64:67]
	s_setprio 0
	s_add_i32 s14, s59, s2
	v_lshl_add_u64 v[210:211], v[210:211], 0, s[22:23]
	s_mov_b32 m0, s14
	ds_read_b128 v[182:185], v149 offset:49152
	ds_read_b128 v[186:189], v149 offset:50176
	ds_read_b128 v[190:193], v149 offset:51200
	ds_read_b128 v[194:197], v149 offset:52224
	ds_read_b128 v[198:201], v149 offset:53248
	ds_read_b128 v[202:205], v149 offset:54272
	ds_read_b128 v[206:209], v149 offset:55296
	ds_read_b128 v[214:217], v149 offset:56320
	global_load_lds_dwordx4 v[210:211], off
	s_add_i32 m0, s14, 0x2000
	s_add_u32 s14, s40, 0x40080
	v_lshl_add_u64 v[210:211], v[218:219], 0, s[22:23]
	s_addc_u32 s15, s41, 0
	s_add_i32 s40, s61, s2
	global_load_lds_dwordx4 v[210:211], off
	v_lshl_add_u64 v[210:211], s[14:15], 0, v[212:213]
	s_mov_b32 m0, s40
	s_nop 0
	global_load_lds_dwordx4 v[210:211], off
	v_lshl_add_u64 v[210:211], s[14:15], 0, v[128:129]
	s_add_i32 m0, s40, 0x2000
	s_nop 0
	global_load_lds_dwordx4 v[210:211], off
	v_lshl_add_u64 v[210:211], v[220:221], 0, s[22:23]
	s_mov_b32 m0, s25
	s_nop 0
	global_load_lds_dwordx4 v[210:211], off
	v_lshl_add_u64 v[210:211], v[222:223], 0, s[22:23]
	s_mov_b32 m0, s27
	s_nop 0
	global_load_lds_dwordx4 v[210:211], off
	s_waitcnt vmcnt(8)
	s_waitcnt lgkmcnt(0)
	s_barrier
	s_setprio 1
	s_waitcnt lgkmcnt(0)
	v_mfma_f32_16x16x32_bf16 v[60:63], v[150:153], v[182:185], v[60:63]
	v_mfma_f32_16x16x32_bf16 v[52:55], v[158:161], v[182:185], v[52:55]
	v_mfma_f32_16x16x32_bf16 v[44:47], v[150:153], v[190:193], v[44:47]
	v_mfma_f32_16x16x32_bf16 v[36:39], v[158:161], v[190:193], v[36:39]
	v_mfma_f32_16x16x32_bf16 v[28:31], v[150:153], v[198:201], v[28:31]
	v_mfma_f32_16x16x32_bf16 v[20:23], v[158:161], v[198:201], v[20:23]
	v_mfma_f32_16x16x32_bf16 v[12:15], v[150:153], v[206:209], v[12:15]
	v_mfma_f32_16x16x32_bf16 v[4:7], v[158:161], v[206:209], v[4:7]
	v_mfma_f32_16x16x32_bf16 v[60:63], v[154:157], v[186:189], v[60:63]
	v_mfma_f32_16x16x32_bf16 v[52:55], v[162:165], v[186:189], v[52:55]
	v_mfma_f32_16x16x32_bf16 v[44:47], v[154:157], v[194:197], v[44:47]
	v_mfma_f32_16x16x32_bf16 v[36:39], v[162:165], v[194:197], v[36:39]
	v_mfma_f32_16x16x32_bf16 v[28:31], v[154:157], v[202:205], v[28:31]
	v_mfma_f32_16x16x32_bf16 v[20:23], v[162:165], v[202:205], v[20:23]
	v_mfma_f32_16x16x32_bf16 v[12:15], v[154:157], v[214:217], v[12:15]
	v_mfma_f32_16x16x32_bf16 v[4:7], v[162:165], v[214:217], v[4:7]
	s_setprio 0
	s_setprio 1
	v_mfma_f32_16x16x32_bf16 v[56:59], v[166:169], v[182:185], v[56:59]
	v_mfma_f32_16x16x32_bf16 v[48:51], v[174:177], v[182:185], v[48:51]
	v_mfma_f32_16x16x32_bf16 v[40:43], v[166:169], v[190:193], v[40:43]
	v_mfma_f32_16x16x32_bf16 v[32:35], v[174:177], v[190:193], v[32:35]
	v_mfma_f32_16x16x32_bf16 v[24:27], v[166:169], v[198:201], v[24:27]
	v_mfma_f32_16x16x32_bf16 v[16:19], v[174:177], v[198:201], v[16:19]
	v_mfma_f32_16x16x32_bf16 v[8:11], v[166:169], v[206:209], v[8:11]
	v_mfma_f32_16x16x32_bf16 v[0:3], v[174:177], v[206:209], v[0:3]
	v_mfma_f32_16x16x32_bf16 v[56:59], v[170:173], v[186:189], v[56:59]
	v_mfma_f32_16x16x32_bf16 v[48:51], v[178:181], v[186:189], v[48:51]
	v_mfma_f32_16x16x32_bf16 v[40:43], v[170:173], v[194:197], v[40:43]
	v_mfma_f32_16x16x32_bf16 v[32:35], v[178:181], v[194:197], v[32:35]
	v_mfma_f32_16x16x32_bf16 v[24:27], v[170:173], v[202:205], v[24:27]
	v_mfma_f32_16x16x32_bf16 v[16:19], v[178:181], v[202:205], v[16:19]
	v_mfma_f32_16x16x32_bf16 v[8:11], v[170:173], v[214:217], v[8:11]
	s_barrier
	v_mfma_f32_16x16x32_bf16 v[0:3], v[178:181], v[214:217], v[0:3]
	s_setprio 0
	s_nop 7
	s_add_i32 s52, s52, 2
	s_add_u32 s68, s68, 0x100
	s_addc_u32 s69, s69, 0
	s_add_u32 s36, s36, 0x100
	s_addc_u32 s37, s37, 0
	s_cmp_gt_u32 s52, 13
	s_cbranch_scc0 .LBB0_369
	s_and_b64 vcc, exec, s[56:57]
	s_cbranch_vccz .LBB0_372
	s_barrier
